# MERGE branch-GEMM epilogue rewritten by hand: 16 gate loads issued up front with counted vmcnt instead of serialized load/wait
# speedup vs baseline: 1.0476x; 1.0175x over previous
; #define G_STAGE(bufoff, gbase, o0, h64) do { \
;         __builtin_amdgcn_global_load_lds((const unsigned*)((const char*)(gbase) + (o0)), (LAS unsigned*)(lds + (bufoff) + ldsw), 16, 0, 0); \
;         __builtin_amdgcn_global_load_lds((const unsigned*)((const char*)(gbase) + (h64) + (o0)), (LAS unsigned*)(lds + (bufoff) + ldsw + 8192), 16, 0, 0); } while (0)
; #define G_LDA(dst, b, h) do { _Pragma("unroll") for (int m = 0; m < 4; ++m) _Pragma("unroll") for (int k = 0; k < 2; ++k) dst[m][k] = *(const LAS bf16x8*)(lds + G_SA(b, h) + aoff + m * 2048 + k * 1024); } while (0)
; #define G_LDB(dst, b, h) do { _Pragma("unroll") for (int n = 0; n < 2; ++n) _Pragma("unroll") for (int k = 0; k < 2; ++k) dst[n][k] = *(const LAS bf16x8*)(lds + G_SB(b, h) + boff + n * 2048 + k * 1024); } while (0)
; #define G_WAIT_L(n) asm volatile("s_waitcnt lgkmcnt(" #n ")" ::: "memory")
; #define G_BAR __builtin_amdgcn_s_barrier()
; #define G_SCHED __builtin_amdgcn_sched_barrier(0)
;     ...
;         for (int t = 0; t < nt; t += 2) {
;             const bool last = (t == nt - 2);
;             const char* a1 = cA + (size_t)(t + 1) * ckA;
;             const char* a2 = last ? nA : cA + (size_t)(t + 2) * ckA; const char* b2 = last ? nB : cB + (size_t)(t + 2) * kB;
;             const char* a3 = a2 + ckA; const char* b3 = b2 + kB;
;             G_LDB(B0, 0, 0); G_SCHED; G_LDA(At, 0, 0); G_STAGE(G_SA(1, 1), a1 + chA, cA0, qA);
;             G_WAIT_L(8); G_BAR; G_WAIT_L(0); G_MMA(0, 0, At, B0); G_BAR; G_SCHED;
;             G_LDB(B1, 0, 1); G_STAGE(G_SB(0, 0), b2, cB0, qB);
;             G_BAR; G_WAIT_L(0); G_MMA(0, 1, At, B1); G_BAR;
;             G_LDA(At, 0, 1); G_STAGE(G_SA(0, 0), a2, cA0, qA);
;             G_BAR; G_WAIT_L(0); G_MMA(1, 0, At, B0); G_BAR; G_SCHED;
.LBB0_890:
	s_add_u32 s4, s6, 0xfff50080
	s_addc_u32 s5, s7, -1
	s_add_i32 s19, 0, 0x10000
	v_add_u32_e32 v0, s19, v175
	ds_read_b128 v[136:139], v0
	ds_read_b128 v[140:143], v0 offset:1024
	ds_read_b128 v[144:147], v0 offset:2048
	ds_read_b128 v[148:151], v0 offset:3072
	s_cmp_eq_u32 s18, 4
	s_cselect_b32 s45, s15, s9
	s_cselect_b32 s44, s14, s8
	s_cselect_b32 s5, s13, s5
	s_cselect_b32 s4, s12, s4
	v_lshl_add_u64 v[2:3], s[6:7], 0, v[156:157]
	s_add_i32 m0, s22, 0xc000
	ds_read_b128 v[158:161], v176
	ds_read_b128 v[162:165], v176 offset:1024
	ds_read_b128 v[178:181], v176 offset:2048
	ds_read_b128 v[182:185], v176 offset:3072
	ds_read_b128 v[196:199], v176 offset:4096
	ds_read_b128 v[200:203], v176 offset:5120
	ds_read_b128 v[204:207], v176 offset:6144
	ds_read_b128 v[208:211], v176 offset:7168
	global_load_lds_dwordx4 v[2:3], off
	v_lshl_add_u64 v[2:3], v[2:3], 0, s[86:87]
	s_add_i32 m0, s22, 0xe000
	s_nop 0
	global_load_lds_dwordx4 v[2:3], off
	s_waitcnt lgkmcnt(8)
	s_barrier
	s_waitcnt lgkmcnt(0)
	s_setprio 3
	s_waitcnt lgkmcnt(0)
	v_mfma_f32_16x16x32_bf16 v[104:107], v[136:139], v[158:161], v[104:107]
	v_mfma_f32_16x16x32_bf16 v[108:111], v[144:147], v[158:161], v[108:111]
	v_mfma_f32_16x16x32_bf16 v[132:135], v[136:139], v[178:181], v[132:135]
	v_mfma_f32_16x16x32_bf16 v[128:131], v[144:147], v[178:181], v[128:131]
	v_mfma_f32_16x16x32_bf16 v[124:127], v[136:139], v[196:199], v[124:127]
	v_mfma_f32_16x16x32_bf16 v[120:123], v[144:147], v[196:199], v[120:123]
	v_mfma_f32_16x16x32_bf16 v[116:119], v[136:139], v[204:207], v[116:119]
	v_mfma_f32_16x16x32_bf16 v[112:115], v[144:147], v[204:207], v[112:115]
	v_mfma_f32_16x16x32_bf16 v[104:107], v[140:143], v[162:165], v[104:107]
	v_mfma_f32_16x16x32_bf16 v[108:111], v[148:151], v[162:165], v[108:111]
	v_mfma_f32_16x16x32_bf16 v[132:135], v[140:143], v[182:185], v[132:135]
	v_mfma_f32_16x16x32_bf16 v[128:131], v[148:151], v[182:185], v[128:131]
	v_mfma_f32_16x16x32_bf16 v[124:127], v[140:143], v[200:203], v[124:127]
	v_mfma_f32_16x16x32_bf16 v[120:123], v[148:151], v[200:203], v[120:123]
	v_mfma_f32_16x16x32_bf16 v[116:119], v[140:143], v[208:211], v[116:119]
	v_mfma_f32_16x16x32_bf16 v[112:115], v[148:151], v[208:211], v[112:115]
	s_setprio 0
	s_barrier
	s_add_i32 s43, 0, 0x14000
	s_add_i32 s19, s19, s21
	v_add_u32_e32 v0, s43, v175
	v_lshl_add_u64 v[2:3], s[44:45], 0, v[154:155]
	s_mov_b64 s[44:45], 0x10000
	s_mov_b32 m0, s19
	ds_read_b128 v[212:215], v0
	ds_read_b128 v[216:219], v0 offset:1024
	ds_read_b128 v[220:223], v0 offset:2048
	ds_read_b128 v[224:227], v0 offset:3072
	global_load_lds_dwordx4 v[2:3], off
	v_lshl_add_u64 v[166:167], v[2:3], 0, s[44:45]
	s_add_i32 m0, s19, 0x2000
	s_nop 0
	global_load_lds_dwordx4 v[166:167], off
	s_barrier
	s_waitcnt lgkmcnt(0)
	s_setprio 3
	s_waitcnt lgkmcnt(0)
	v_mfma_f32_16x16x32_bf16 v[100:103], v[212:215], v[158:161], v[100:103]
	v_mfma_f32_16x16x32_bf16 v[96:99], v[220:223], v[158:161], v[96:99]
	v_mfma_f32_16x16x32_bf16 v[92:95], v[212:215], v[178:181], v[92:95]
	v_mfma_f32_16x16x32_bf16 v[88:91], v[220:223], v[178:181], v[88:91]
	v_mfma_f32_16x16x32_bf16 v[84:87], v[212:215], v[196:199], v[84:87]
	v_mfma_f32_16x16x32_bf16 v[80:83], v[220:223], v[196:199], v[80:83]
	v_mfma_f32_16x16x32_bf16 v[76:79], v[212:215], v[204:207], v[76:79]
	v_mfma_f32_16x16x32_bf16 v[72:75], v[220:223], v[204:207], v[72:75]
	v_mfma_f32_16x16x32_bf16 v[100:103], v[216:219], v[162:165], v[100:103]
	v_mfma_f32_16x16x32_bf16 v[96:99], v[224:227], v[162:165], v[96:99]
	v_mfma_f32_16x16x32_bf16 v[92:95], v[216:219], v[182:185], v[92:95]
	v_mfma_f32_16x16x32_bf16 v[88:91], v[224:227], v[182:185], v[88:91]
	v_mfma_f32_16x16x32_bf16 v[84:87], v[216:219], v[200:203], v[84:87]
	v_mfma_f32_16x16x32_bf16 v[80:83], v[224:227], v[200:203], v[80:83]
	v_mfma_f32_16x16x32_bf16 v[76:79], v[216:219], v[208:211], v[76:79]
	v_mfma_f32_16x16x32_bf16 v[72:75], v[224:227], v[208:211], v[72:75]
	s_setprio 0
	s_mov_b32 m0, s22
	v_lshl_add_u64 v[166:167], s[4:5], 0, v[152:153]
	s_barrier
	ds_read_b128 v[158:161], v176 offset:16384
	ds_read_b128 v[162:165], v176 offset:17408
	ds_read_b128 v[178:181], v176 offset:18432
	ds_read_b128 v[182:185], v176 offset:19456
	ds_read_b128 v[196:199], v176 offset:20480
	ds_read_b128 v[200:203], v176 offset:21504
	ds_read_b128 v[204:207], v176 offset:22528
	ds_read_b128 v[208:211], v176 offset:23552
	global_load_lds_dwordx4 v[166:167], off
	v_lshl_add_u64 v[172:173], v[166:167], 0, s[86:87]
	s_mov_b32 m0, s23
	s_nop 0
	global_load_lds_dwordx4 v[172:173], off
	s_barrier
	s_waitcnt lgkmcnt(0)
	s_setprio 3
	s_waitcnt lgkmcnt(0)
	v_mfma_f32_16x16x32_bf16 v[68:71], v[136:139], v[158:161], v[68:71]
	v_mfma_f32_16x16x32_bf16 v[64:67], v[144:147], v[158:161], v[64:67]
	v_mfma_f32_16x16x32_bf16 v[60:63], v[136:139], v[178:181], v[60:63]
	v_mfma_f32_16x16x32_bf16 v[56:59], v[144:147], v[178:181], v[56:59]
	v_mfma_f32_16x16x32_bf16 v[52:55], v[136:139], v[196:199], v[52:55]
	v_mfma_f32_16x16x32_bf16 v[48:51], v[144:147], v[196:199], v[48:51]
	v_mfma_f32_16x16x32_bf16 v[44:47], v[136:139], v[204:207], v[44:47]
	v_mfma_f32_16x16x32_bf16 v[40:43], v[144:147], v[204:207], v[40:43]
	v_mfma_f32_16x16x32_bf16 v[68:71], v[140:143], v[162:165], v[68:71]
	v_mfma_f32_16x16x32_bf16 v[64:67], v[148:151], v[162:165], v[64:67]
	v_mfma_f32_16x16x32_bf16 v[60:63], v[140:143], v[182:185], v[60:63]
	v_mfma_f32_16x16x32_bf16 v[56:59], v[148:151], v[182:185], v[56:59]
	v_mfma_f32_16x16x32_bf16 v[52:55], v[140:143], v[200:203], v[52:55]
	v_mfma_f32_16x16x32_bf16 v[48:51], v[148:151], v[200:203], v[48:51]
	v_mfma_f32_16x16x32_bf16 v[44:47], v[140:143], v[208:211], v[44:47]
	v_mfma_f32_16x16x32_bf16 v[40:43], v[148:151], v[208:211], v[40:43]
	s_setprio 0
	s_barrier
; #define G_STAGE(bufoff, gbase, o0, h64) do { \
;         __builtin_amdgcn_global_load_lds((const unsigned*)((const char*)(gbase) + (o0)), (LAS unsigned*)(lds + (bufoff) + ldsw), 16, 0, 0); \
;         __builtin_amdgcn_global_load_lds((const unsigned*)((const char*)(gbase) + (h64) + (o0)), (LAS unsigned*)(lds + (bufoff) + ldsw + 8192), 16, 0, 0); } while (0)
; #define G_LDA(dst, b, h) do { _Pragma("unroll") for (int m = 0; m < 4; ++m) _Pragma("unroll") for (int k = 0; k < 2; ++k) dst[m][k] = *(const LAS bf16x8*)(lds + G_SA(b, h) + aoff + m * 2048 + k * 1024); } while (0)
; #define G_LDB(dst, b, h) do { _Pragma("unroll") for (int n = 0; n < 2; ++n) _Pragma("unroll") for (int k = 0; k < 2; ++k) dst[n][k] = *(const LAS bf16x8*)(lds + G_SB(b, h) + boff + n * 2048 + k * 1024); } while (0)
; #define G_WAIT_V(n) asm volatile("s_waitcnt vmcnt(" #n ")" ::: "memory")
; #define G_WAIT_L(n) asm volatile("s_waitcnt lgkmcnt(" #n ")" ::: "memory")
; #define G_BAR __builtin_amdgcn_s_barrier()
; #define G_SCHED __builtin_amdgcn_sched_barrier(0)
;     ...
;             G_STAGE(G_SB(0, 1), b2 + chB, cB0, qB);
;             G_WAIT_V(6); G_BAR; G_MMA(1, 1, At, B1); G_BAR;
;             G_LDB(B0, 1, 0); G_SCHED; G_LDA(At, 1, 0); G_STAGE(G_SA(0, 1), a2 + chA, cA0, qA);
;             G_WAIT_L(8); G_BAR; G_WAIT_L(0); G_MMA(0, 0, At, B0); G_BAR; G_SCHED;
;             G_LDB(B1, 1, 1); G_STAGE(G_SB(1, 0), b3, cB0, qB);
;             G_BAR; G_WAIT_L(0); G_MMA(0, 1, At, B1); G_BAR;
;             G_LDA(At, 1, 1); G_STAGE(G_SA(1, 0), a3, cA0, qA);
	s_add_i32 s4, s43, s21
	v_lshl_add_u64 v[136:137], v[2:3], 0, s[0:1]
	s_mov_b32 m0, s4
	s_nop 0
	global_load_lds_dwordx4 v[136:137], off
	v_lshl_add_u64 v[136:137], v[2:3], 0, s[52:53]
	s_add_i32 m0, s4, 0x2000
	s_nop 0
	global_load_lds_dwordx4 v[136:137], off
	s_waitcnt vmcnt(6)
	s_barrier
	s_setprio 3
	v_mfma_f32_16x16x32_bf16 v[36:39], v[212:215], v[158:161], v[36:39]
	v_mfma_f32_16x16x32_bf16 v[32:35], v[220:223], v[158:161], v[32:35]
	v_mfma_f32_16x16x32_bf16 v[28:31], v[212:215], v[178:181], v[28:31]
	v_mfma_f32_16x16x32_bf16 v[24:27], v[220:223], v[178:181], v[24:27]
	v_mfma_f32_16x16x32_bf16 v[20:23], v[212:215], v[196:199], v[20:23]
	v_mfma_f32_16x16x32_bf16 v[16:19], v[220:223], v[196:199], v[16:19]
	v_mfma_f32_16x16x32_bf16 v[12:15], v[212:215], v[204:207], v[12:15]
	v_mfma_f32_16x16x32_bf16 v[8:11], v[220:223], v[204:207], v[8:11]
	v_mfma_f32_16x16x32_bf16 v[36:39], v[216:219], v[162:165], v[36:39]
	v_mfma_f32_16x16x32_bf16 v[32:35], v[224:227], v[162:165], v[32:35]
	v_mfma_f32_16x16x32_bf16 v[28:31], v[216:219], v[182:185], v[28:31]
	v_mfma_f32_16x16x32_bf16 v[24:27], v[224:227], v[182:185], v[24:27]
	v_mfma_f32_16x16x32_bf16 v[20:23], v[216:219], v[200:203], v[20:23]
	v_mfma_f32_16x16x32_bf16 v[16:19], v[224:227], v[200:203], v[16:19]
	v_mfma_f32_16x16x32_bf16 v[12:15], v[216:219], v[208:211], v[12:15]
	v_mfma_f32_16x16x32_bf16 v[8:11], v[224:227], v[208:211], v[8:11]
	s_setprio 0
	s_add_i32 s4, 0, 0x18000
	v_add_u32_e32 v0, s4, v175
	s_barrier
	ds_read_b128 v[136:139], v0
	ds_read_b128 v[140:143], v0 offset:1024
	ds_read_b128 v[144:147], v0 offset:2048
	ds_read_b128 v[148:151], v0 offset:3072
	s_mov_b32 m0, s24
	v_lshl_add_u64 v[172:173], v[166:167], 0, s[88:89]
	ds_read_b128 v[158:161], v176 offset:32768
	ds_read_b128 v[162:165], v176 offset:33792
	ds_read_b128 v[178:181], v176 offset:34816
	ds_read_b128 v[182:185], v176 offset:35840
	ds_read_b128 v[196:199], v176 offset:36864
	ds_read_b128 v[200:203], v176 offset:37888
	ds_read_b128 v[204:207], v176 offset:38912
	ds_read_b128 v[208:211], v176 offset:39936
	global_load_lds_dwordx4 v[172:173], off
	v_lshl_add_u64 v[172:173], v[166:167], 0, s[64:65]
	s_mov_b32 m0, s25
	s_nop 0
	global_load_lds_dwordx4 v[172:173], off
	s_waitcnt lgkmcnt(8)
	s_barrier
	s_waitcnt lgkmcnt(0)
	s_setprio 3
	s_waitcnt lgkmcnt(0)
	v_mfma_f32_16x16x32_bf16 v[104:107], v[136:139], v[158:161], v[104:107]
	v_mfma_f32_16x16x32_bf16 v[108:111], v[144:147], v[158:161], v[108:111]
	v_mfma_f32_16x16x32_bf16 v[132:135], v[136:139], v[178:181], v[132:135]
	v_mfma_f32_16x16x32_bf16 v[128:131], v[144:147], v[178:181], v[128:131]
	v_mfma_f32_16x16x32_bf16 v[124:127], v[136:139], v[196:199], v[124:127]
	v_mfma_f32_16x16x32_bf16 v[120:123], v[144:147], v[196:199], v[120:123]
	v_mfma_f32_16x16x32_bf16 v[116:119], v[136:139], v[204:207], v[116:119]
	v_mfma_f32_16x16x32_bf16 v[112:115], v[144:147], v[204:207], v[112:115]
	v_mfma_f32_16x16x32_bf16 v[104:107], v[140:143], v[162:165], v[104:107]
	v_mfma_f32_16x16x32_bf16 v[108:111], v[148:151], v[162:165], v[108:111]
	v_mfma_f32_16x16x32_bf16 v[132:135], v[140:143], v[182:185], v[132:135]
	v_mfma_f32_16x16x32_bf16 v[128:131], v[148:151], v[182:185], v[128:131]
	v_mfma_f32_16x16x32_bf16 v[124:127], v[140:143], v[200:203], v[124:127]
	v_mfma_f32_16x16x32_bf16 v[120:123], v[148:151], v[200:203], v[120:123]
	v_mfma_f32_16x16x32_bf16 v[116:119], v[140:143], v[208:211], v[116:119]
	v_mfma_f32_16x16x32_bf16 v[112:115], v[148:151], v[208:211], v[112:115]
	s_setprio 0
	s_barrier
	s_add_i32 s5, 0, 0x1c000
	s_add_i32 s4, s4, s21
	v_add_u32_e32 v0, s5, v175
	v_lshl_add_u64 v[172:173], v[2:3], 0, s[46:47]
	s_mov_b32 m0, s4
	ds_read_b128 v[212:215], v0
	ds_read_b128 v[216:219], v0 offset:1024
	ds_read_b128 v[220:223], v0 offset:2048
	ds_read_b128 v[224:227], v0 offset:3072
	global_load_lds_dwordx4 v[172:173], off
	v_lshl_add_u64 v[172:173], v[2:3], 0, s[54:55]
	s_add_i32 m0, s4, 0x2000
	s_nop 0
	global_load_lds_dwordx4 v[172:173], off
	s_barrier
	s_waitcnt lgkmcnt(0)
	s_setprio 3
	s_waitcnt lgkmcnt(0)
	v_mfma_f32_16x16x32_bf16 v[100:103], v[212:215], v[158:161], v[100:103]
	v_mfma_f32_16x16x32_bf16 v[96:99], v[220:223], v[158:161], v[96:99]
	v_mfma_f32_16x16x32_bf16 v[92:95], v[212:215], v[178:181], v[92:95]
	v_mfma_f32_16x16x32_bf16 v[88:91], v[220:223], v[178:181], v[88:91]
	v_mfma_f32_16x16x32_bf16 v[84:87], v[212:215], v[196:199], v[84:87]
	v_mfma_f32_16x16x32_bf16 v[80:83], v[220:223], v[196:199], v[80:83]
	v_mfma_f32_16x16x32_bf16 v[76:79], v[212:215], v[204:207], v[76:79]
	v_mfma_f32_16x16x32_bf16 v[72:75], v[220:223], v[204:207], v[72:75]
	v_mfma_f32_16x16x32_bf16 v[100:103], v[216:219], v[162:165], v[100:103]
	v_mfma_f32_16x16x32_bf16 v[96:99], v[224:227], v[162:165], v[96:99]
	v_mfma_f32_16x16x32_bf16 v[92:95], v[216:219], v[182:185], v[92:95]
	v_mfma_f32_16x16x32_bf16 v[88:91], v[224:227], v[182:185], v[88:91]
	v_mfma_f32_16x16x32_bf16 v[84:87], v[216:219], v[200:203], v[84:87]
	v_mfma_f32_16x16x32_bf16 v[80:83], v[224:227], v[200:203], v[80:83]
	v_mfma_f32_16x16x32_bf16 v[76:79], v[216:219], v[208:211], v[76:79]
	v_mfma_f32_16x16x32_bf16 v[72:75], v[224:227], v[208:211], v[72:75]
	s_setprio 0
	s_mov_b32 m0, s26
	v_lshl_add_u64 v[172:173], v[166:167], 0, s[46:47]
	s_barrier
	ds_read_b128 v[158:161], v176 offset:49152
	ds_read_b128 v[162:165], v176 offset:50176
	ds_read_b128 v[178:181], v176 offset:51200
	ds_read_b128 v[182:185], v176 offset:52224
	ds_read_b128 v[196:199], v176 offset:53248
	ds_read_b128 v[200:203], v176 offset:54272
	ds_read_b128 v[204:207], v176 offset:55296
	ds_read_b128 v[208:211], v176 offset:56320
	global_load_lds_dwordx4 v[172:173], off
	v_lshl_add_u64 v[166:167], v[166:167], 0, s[66:67]
	s_mov_b32 m0, s27
	s_nop 0
	global_load_lds_dwordx4 v[166:167], off
	s_barrier
; #define G_STAGE(bufoff, gbase, o0, h64) do { \
;         __builtin_amdgcn_global_load_lds((const unsigned*)((const char*)(gbase) + (o0)), (LAS unsigned*)(lds + (bufoff) + ldsw), 16, 0, 0); \
;         __builtin_amdgcn_global_load_lds((const unsigned*)((const char*)(gbase) + (h64) + (o0)), (LAS unsigned*)(lds + (bufoff) + ldsw + 8192), 16, 0, 0); } while (0)
; #define G_WAIT_V(n) asm volatile("s_waitcnt vmcnt(" #n ")" ::: "memory")
; #define G_WAIT_L(n) asm volatile("s_waitcnt lgkmcnt(" #n ")" ::: "memory")
; #define G_BAR __builtin_amdgcn_s_barrier()
; #define G_SCHED __builtin_amdgcn_sched_barrier(0)
;     template <int KIND> __device__ __forceinline__ void run(f32x4 (&acc)[2][2][4][2], const Unit& u, int tid_in) const {
;     ...
;         if constexpr (KIND == K_MG_B) { const int r = u.aux;
;             const u32x4* gst = (const u32x4*)((unsigned char*)x + 32 * MiB) + ((size_t)(blockIdx.x * 2 + (u.ord & 1)) * 3) * 4096;
; #pragma unroll
;             for (int ai = 0; ai < 2; ++ai)
; #pragma unroll
;                 for (int mh = 0; mh < 2; ++mh) { u32x4 qa[2], qb[2];
; #pragma unroll
;                     for (int ml = 0; ml < 2; ++ml) { const int m = mh * 2 + ml; qa[ml] = gst[(size_t)r * 4096 + (ai * 4 + m) * 512 + tid]; qb[ml] = (r < 2) ? gst[(size_t)(r + 1) * 4096 + (ai * 4 + m) * 512 + tid] : qa[ml]; }
;     ...
;             G_BAR; G_WAIT_L(0); G_MMA(1, 0, At, B0); G_BAR; G_SCHED;
;             G_STAGE(G_SB(1, 1), b3 + chB, cB0, qB);
;             G_WAIT_V(6); G_BAR; G_MMA(1, 1, At, B1); G_BAR;
;         }
	s_waitcnt lgkmcnt(0)
	s_setprio 3
	s_waitcnt lgkmcnt(0)
	v_mfma_f32_16x16x32_bf16 v[68:71], v[136:139], v[158:161], v[68:71]
	v_mfma_f32_16x16x32_bf16 v[64:67], v[144:147], v[158:161], v[64:67]
	v_mfma_f32_16x16x32_bf16 v[60:63], v[136:139], v[178:181], v[60:63]
	v_mfma_f32_16x16x32_bf16 v[56:59], v[144:147], v[178:181], v[56:59]
	v_mfma_f32_16x16x32_bf16 v[52:55], v[136:139], v[196:199], v[52:55]
	v_mfma_f32_16x16x32_bf16 v[48:51], v[144:147], v[196:199], v[48:51]
	v_mfma_f32_16x16x32_bf16 v[44:47], v[136:139], v[204:207], v[44:47]
	v_mfma_f32_16x16x32_bf16 v[40:43], v[144:147], v[204:207], v[40:43]
	v_mfma_f32_16x16x32_bf16 v[68:71], v[140:143], v[162:165], v[68:71]
	v_mfma_f32_16x16x32_bf16 v[64:67], v[148:151], v[162:165], v[64:67]
	v_mfma_f32_16x16x32_bf16 v[60:63], v[140:143], v[182:185], v[60:63]
	v_mfma_f32_16x16x32_bf16 v[56:59], v[148:151], v[182:185], v[56:59]
	v_mfma_f32_16x16x32_bf16 v[52:55], v[140:143], v[200:203], v[52:55]
	v_mfma_f32_16x16x32_bf16 v[48:51], v[148:151], v[200:203], v[48:51]
	v_mfma_f32_16x16x32_bf16 v[44:47], v[140:143], v[208:211], v[44:47]
	v_mfma_f32_16x16x32_bf16 v[40:43], v[148:151], v[208:211], v[40:43]
	s_setprio 0
	s_barrier
	s_add_i32 s4, s5, s21
	v_lshl_add_u64 v[136:137], v[2:3], 0, s[50:51]
	s_mov_b32 m0, s4
	v_lshl_add_u64 v[2:3], v[2:3], 0, s[58:59]
	global_load_lds_dwordx4 v[136:137], off
	s_add_i32 m0, s4, 0x2000
	s_nop 0
	global_load_lds_dwordx4 v[2:3], off
	s_waitcnt vmcnt(6)
	s_barrier
	s_setprio 3
	v_mfma_f32_16x16x32_bf16 v[36:39], v[212:215], v[158:161], v[36:39]
	v_mfma_f32_16x16x32_bf16 v[32:35], v[220:223], v[158:161], v[32:35]
	v_mfma_f32_16x16x32_bf16 v[28:31], v[212:215], v[178:181], v[28:31]
	v_mfma_f32_16x16x32_bf16 v[24:27], v[220:223], v[178:181], v[24:27]
	v_mfma_f32_16x16x32_bf16 v[20:23], v[212:215], v[196:199], v[20:23]
	v_mfma_f32_16x16x32_bf16 v[16:19], v[220:223], v[196:199], v[16:19]
	v_mfma_f32_16x16x32_bf16 v[12:15], v[212:215], v[204:207], v[12:15]
	v_mfma_f32_16x16x32_bf16 v[8:11], v[220:223], v[204:207], v[8:11]
	v_mfma_f32_16x16x32_bf16 v[36:39], v[216:219], v[162:165], v[36:39]
	v_mfma_f32_16x16x32_bf16 v[32:35], v[224:227], v[162:165], v[32:35]
	v_mfma_f32_16x16x32_bf16 v[28:31], v[216:219], v[182:185], v[28:31]
	v_mfma_f32_16x16x32_bf16 v[24:27], v[224:227], v[182:185], v[24:27]
	v_mfma_f32_16x16x32_bf16 v[20:23], v[216:219], v[200:203], v[20:23]
	v_mfma_f32_16x16x32_bf16 v[16:19], v[224:227], v[200:203], v[16:19]
	v_mfma_f32_16x16x32_bf16 v[12:15], v[216:219], v[208:211], v[12:15]
	v_mfma_f32_16x16x32_bf16 v[8:11], v[224:227], v[208:211], v[8:11]
	s_setprio 0
	s_add_i32 s18, s18, 2
	s_add_u32 s6, s6, 0x100
	s_addc_u32 s7, s7, 0
	s_add_u32 s8, s8, 0x100
	s_addc_u32 s9, s9, 0
	s_cmp_gt_u32 s18, 5
	s_barrier
	s_cbranch_scc0 .LBB0_890
	s_and_b32 s3, s3, 1
	s_or_b32 s3, s3, s60
	s_mul_hi_u32 s4, s3, 0x30000
	s_mul_i32 s3, s3, 0x30000
	s_add_u32 s6, s35, s3
	s_addc_u32 s7, s36, s4
	s_ashr_i32 s3, s2, 31
	s_lshl_b64 s[4:5], s[2:3], 16
	s_add_u32 s4, s6, s4
	s_addc_u32 s5, s7, s5
	v_lshlrev_b32_e32 v166, 4, v174
	s_cmp_gt_i32 s2, 1
	s_cbranch_scc1 .Lmg1_r2
	s_add_u32 s8, s4, 0x10000
	s_addc_u32 s9, s5, 0
	global_load_dwordx4 v[136:139], v166, s[4:5]
	global_load_dwordx4 v[212:215], v166, s[8:9]
	s_add_u32 s4, s4, 0x2000
	s_addc_u32 s5, s5, 0
	s_add_u32 s8, s8, 0x2000
	s_addc_u32 s9, s9, 0
	global_load_dwordx4 v[140:143], v166, s[4:5]
	global_load_dwordx4 v[216:219], v166, s[8:9]
	s_add_u32 s4, s4, 0x2000
	s_addc_u32 s5, s5, 0
	s_add_u32 s8, s8, 0x2000
	s_addc_u32 s9, s9, 0
	global_load_dwordx4 v[144:147], v166, s[4:5]
	global_load_dwordx4 v[220:223], v166, s[8:9]
	s_add_u32 s4, s4, 0x2000
	s_addc_u32 s5, s5, 0
	s_add_u32 s8, s8, 0x2000
	s_addc_u32 s9, s9, 0
	global_load_dwordx4 v[148:151], v166, s[4:5]
	global_load_dwordx4 v[224:227], v166, s[8:9]
	s_add_u32 s4, s4, 0x2000
	s_addc_u32 s5, s5, 0
	s_add_u32 s8, s8, 0x2000
	s_addc_u32 s9, s9, 0
	global_load_dwordx4 v[196:199], v166, s[4:5]
	global_load_dwordx4 v[178:181], v166, s[8:9]
	s_add_u32 s4, s4, 0x2000
	s_addc_u32 s5, s5, 0
	s_add_u32 s8, s8, 0x2000
	s_addc_u32 s9, s9, 0
	global_load_dwordx4 v[200:203], v166, s[4:5]
	global_load_dwordx4 v[182:185], v166, s[8:9]
	s_add_u32 s4, s4, 0x2000
	s_addc_u32 s5, s5, 0
	s_add_u32 s8, s8, 0x2000
	s_addc_u32 s9, s9, 0
	global_load_dwordx4 v[204:207], v166, s[4:5]
	global_load_dwordx4 v[158:161], v166, s[8:9]
	s_add_u32 s4, s4, 0x2000
	s_addc_u32 s5, s5, 0
	s_add_u32 s8, s8, 0x2000
	s_addc_u32 s9, s9, 0
	global_load_dwordx4 v[208:211], v166, s[4:5]
	global_load_dwordx4 v[162:165], v166, s[8:9]
	s_waitcnt vmcnt(14)
;     template <int KIND> __device__ __forceinline__ void run(f32x4 (&acc)[2][2][4][2], const Unit& u, int tid_in) const {
;     ...
;                             const f32x4 n0 = unpack4_raw(bj == 0 ? qa[ml].x : qa[ml].z), n1 = unpack4_raw(bj == 0 ? qa[ml].y : qa[ml].w);
;                             if (r < 2) { const f32x4 d0 = unpack4_raw(bj == 0 ? qb[ml].x : qb[ml].z), d1 = unpack4_raw(bj == 0 ? qb[ml].y : qb[ml].w);
; #pragma unroll
;                                 for (int j = 0; j < 4; ++j) { acc[ai][bj][m][0][j] *= n0[j] * __builtin_amdgcn_rcpf(d0[j]); acc[ai][bj][m][1][j] *= n1[j] * __builtin_amdgcn_rcpf(d1[j]); } }
	v_cvt_f32_ubyte0_e32 v240, v136
	v_cvt_f32_ubyte1_e32 v241, v136
	v_cvt_f32_ubyte2_e32 v242, v136
	v_cvt_f32_ubyte3_e32 v243, v136
	v_cvt_f32_ubyte0_e32 v244, v137
	v_cvt_f32_ubyte1_e32 v245, v137
	v_cvt_f32_ubyte2_e32 v246, v137
	v_cvt_f32_ubyte3_e32 v247, v137
	v_cvt_f32_ubyte0_e32 v248, v212
	v_cvt_f32_ubyte1_e32 v249, v212
	v_cvt_f32_ubyte2_e32 v250, v212
	v_cvt_f32_ubyte3_e32 v251, v212
	v_cvt_f32_ubyte0_e32 v252, v213
	v_cvt_f32_ubyte1_e32 v253, v213
	v_cvt_f32_ubyte2_e32 v254, v213
	v_cvt_f32_ubyte3_e32 v255, v213
	v_rcp_iflag_f32_e32 v248, v248
	v_rcp_iflag_f32_e32 v249, v249
	v_rcp_iflag_f32_e32 v250, v250
	v_rcp_iflag_f32_e32 v251, v251
	v_rcp_iflag_f32_e32 v252, v252
	v_rcp_iflag_f32_e32 v253, v253
	v_rcp_iflag_f32_e32 v254, v254
	v_rcp_iflag_f32_e32 v255, v255
	v_pk_mul_f32 v[240:241], v[248:249], v[240:241]
	v_pk_mul_f32 v[242:243], v[250:251], v[242:243]
	v_pk_mul_f32 v[244:245], v[252:253], v[244:245]
	v_pk_mul_f32 v[246:247], v[254:255], v[246:247]
	v_pk_mul_f32 v[104:105], v[104:105], v[240:241]
	v_pk_mul_f32 v[106:107], v[106:107], v[242:243]
	v_pk_mul_f32 v[108:109], v[108:109], v[244:245]
	v_pk_mul_f32 v[110:111], v[110:111], v[246:247]
	v_cvt_f32_ubyte0_e32 v240, v138
	v_cvt_f32_ubyte1_e32 v241, v138
	v_cvt_f32_ubyte2_e32 v242, v138
	v_cvt_f32_ubyte3_e32 v243, v138
	v_cvt_f32_ubyte0_e32 v244, v139
	v_cvt_f32_ubyte1_e32 v245, v139
	v_cvt_f32_ubyte2_e32 v246, v139
	v_cvt_f32_ubyte3_e32 v247, v139
	v_cvt_f32_ubyte0_e32 v248, v214
	v_cvt_f32_ubyte1_e32 v249, v214
	v_cvt_f32_ubyte2_e32 v250, v214
	v_cvt_f32_ubyte3_e32 v251, v214
	v_cvt_f32_ubyte0_e32 v252, v215
	v_cvt_f32_ubyte1_e32 v253, v215
	v_cvt_f32_ubyte2_e32 v254, v215
	v_cvt_f32_ubyte3_e32 v255, v215
	v_rcp_iflag_f32_e32 v248, v248
	v_rcp_iflag_f32_e32 v249, v249
	v_rcp_iflag_f32_e32 v250, v250
	v_rcp_iflag_f32_e32 v251, v251
	v_rcp_iflag_f32_e32 v252, v252
	v_rcp_iflag_f32_e32 v253, v253
	v_rcp_iflag_f32_e32 v254, v254
	v_rcp_iflag_f32_e32 v255, v255
	v_pk_mul_f32 v[240:241], v[248:249], v[240:241]
	v_pk_mul_f32 v[242:243], v[250:251], v[242:243]
	v_pk_mul_f32 v[244:245], v[252:253], v[244:245]
	v_pk_mul_f32 v[246:247], v[254:255], v[246:247]
	v_pk_mul_f32 v[100:101], v[100:101], v[240:241]
	v_pk_mul_f32 v[102:103], v[102:103], v[242:243]
	v_pk_mul_f32 v[96:97], v[96:97], v[244:245]
	v_pk_mul_f32 v[98:99], v[98:99], v[246:247]
	s_waitcnt vmcnt(12)
	v_cvt_f32_ubyte0_e32 v240, v140
	v_cvt_f32_ubyte1_e32 v241, v140
	v_cvt_f32_ubyte2_e32 v242, v140
	v_cvt_f32_ubyte3_e32 v243, v140
	v_cvt_f32_ubyte0_e32 v244, v141
	v_cvt_f32_ubyte1_e32 v245, v141
	v_cvt_f32_ubyte2_e32 v246, v141
	v_cvt_f32_ubyte3_e32 v247, v141
	v_cvt_f32_ubyte0_e32 v248, v216
	v_cvt_f32_ubyte1_e32 v249, v216
	v_cvt_f32_ubyte2_e32 v250, v216
	v_cvt_f32_ubyte3_e32 v251, v216
	v_cvt_f32_ubyte0_e32 v252, v217
	v_cvt_f32_ubyte1_e32 v253, v217
	v_cvt_f32_ubyte2_e32 v254, v217
	v_cvt_f32_ubyte3_e32 v255, v217
	v_rcp_iflag_f32_e32 v248, v248
	v_rcp_iflag_f32_e32 v249, v249
	v_rcp_iflag_f32_e32 v250, v250
	v_rcp_iflag_f32_e32 v251, v251
	v_rcp_iflag_f32_e32 v252, v252
	v_rcp_iflag_f32_e32 v253, v253
	v_rcp_iflag_f32_e32 v254, v254
	v_rcp_iflag_f32_e32 v255, v255
	v_pk_mul_f32 v[240:241], v[248:249], v[240:241]
	v_pk_mul_f32 v[242:243], v[250:251], v[242:243]
	v_pk_mul_f32 v[244:245], v[252:253], v[244:245]
	v_pk_mul_f32 v[246:247], v[254:255], v[246:247]
	v_pk_mul_f32 v[132:133], v[132:133], v[240:241]
	v_pk_mul_f32 v[134:135], v[134:135], v[242:243]
	v_pk_mul_f32 v[128:129], v[128:129], v[244:245]
	v_pk_mul_f32 v[130:131], v[130:131], v[246:247]
	v_cvt_f32_ubyte0_e32 v240, v142
	v_cvt_f32_ubyte1_e32 v241, v142
	v_cvt_f32_ubyte2_e32 v242, v142
	v_cvt_f32_ubyte3_e32 v243, v142
	v_cvt_f32_ubyte0_e32 v244, v143
	v_cvt_f32_ubyte1_e32 v245, v143
	v_cvt_f32_ubyte2_e32 v246, v143
	v_cvt_f32_ubyte3_e32 v247, v143
	v_cvt_f32_ubyte0_e32 v248, v218
	v_cvt_f32_ubyte1_e32 v249, v218
	v_cvt_f32_ubyte2_e32 v250, v218
	v_cvt_f32_ubyte3_e32 v251, v218
	v_cvt_f32_ubyte0_e32 v252, v219
	v_cvt_f32_ubyte1_e32 v253, v219
	v_cvt_f32_ubyte2_e32 v254, v219
	v_cvt_f32_ubyte3_e32 v255, v219
	v_rcp_iflag_f32_e32 v248, v248
	v_rcp_iflag_f32_e32 v249, v249
	v_rcp_iflag_f32_e32 v250, v250
	v_rcp_iflag_f32_e32 v251, v251
	v_rcp_iflag_f32_e32 v252, v252
	v_rcp_iflag_f32_e32 v253, v253
	v_rcp_iflag_f32_e32 v254, v254
	v_rcp_iflag_f32_e32 v255, v255
	v_pk_mul_f32 v[240:241], v[248:249], v[240:241]
	v_pk_mul_f32 v[242:243], v[250:251], v[242:243]
	v_pk_mul_f32 v[244:245], v[252:253], v[244:245]
	v_pk_mul_f32 v[246:247], v[254:255], v[246:247]
	v_pk_mul_f32 v[92:93], v[92:93], v[240:241]
	v_pk_mul_f32 v[94:95], v[94:95], v[242:243]
	v_pk_mul_f32 v[88:89], v[88:89], v[244:245]
	v_pk_mul_f32 v[90:91], v[90:91], v[246:247]
	s_waitcnt vmcnt(10)
;     template <int KIND> __device__ __forceinline__ void run(f32x4 (&acc)[2][2][4][2], const Unit& u, int tid_in) const {
;     ...
;                             const f32x4 n0 = unpack4_raw(bj == 0 ? qa[ml].x : qa[ml].z), n1 = unpack4_raw(bj == 0 ? qa[ml].y : qa[ml].w);
;                             if (r < 2) { const f32x4 d0 = unpack4_raw(bj == 0 ? qb[ml].x : qb[ml].z), d1 = unpack4_raw(bj == 0 ? qb[ml].y : qb[ml].w);
; #pragma unroll
;                                 for (int j = 0; j < 4; ++j) { acc[ai][bj][m][0][j] *= n0[j] * __builtin_amdgcn_rcpf(d0[j]); acc[ai][bj][m][1][j] *= n1[j] * __builtin_amdgcn_rcpf(d1[j]); } }
	v_cvt_f32_ubyte0_e32 v240, v144
	v_cvt_f32_ubyte1_e32 v241, v144
	v_cvt_f32_ubyte2_e32 v242, v144
	v_cvt_f32_ubyte3_e32 v243, v144
	v_cvt_f32_ubyte0_e32 v244, v145
	v_cvt_f32_ubyte1_e32 v245, v145
	v_cvt_f32_ubyte2_e32 v246, v145
	v_cvt_f32_ubyte3_e32 v247, v145
	v_cvt_f32_ubyte0_e32 v248, v220
	v_cvt_f32_ubyte1_e32 v249, v220
	v_cvt_f32_ubyte2_e32 v250, v220
	v_cvt_f32_ubyte3_e32 v251, v220
	v_cvt_f32_ubyte0_e32 v252, v221
	v_cvt_f32_ubyte1_e32 v253, v221
	v_cvt_f32_ubyte2_e32 v254, v221
	v_cvt_f32_ubyte3_e32 v255, v221
	v_rcp_iflag_f32_e32 v248, v248
	v_rcp_iflag_f32_e32 v249, v249
	v_rcp_iflag_f32_e32 v250, v250
	v_rcp_iflag_f32_e32 v251, v251
	v_rcp_iflag_f32_e32 v252, v252
	v_rcp_iflag_f32_e32 v253, v253
	v_rcp_iflag_f32_e32 v254, v254
	v_rcp_iflag_f32_e32 v255, v255
	v_pk_mul_f32 v[240:241], v[248:249], v[240:241]
	v_pk_mul_f32 v[242:243], v[250:251], v[242:243]
	v_pk_mul_f32 v[244:245], v[252:253], v[244:245]
	v_pk_mul_f32 v[246:247], v[254:255], v[246:247]
	v_pk_mul_f32 v[124:125], v[124:125], v[240:241]
	v_pk_mul_f32 v[126:127], v[126:127], v[242:243]
	v_pk_mul_f32 v[120:121], v[120:121], v[244:245]
	v_pk_mul_f32 v[122:123], v[122:123], v[246:247]
	v_cvt_f32_ubyte0_e32 v240, v146
	v_cvt_f32_ubyte1_e32 v241, v146
	v_cvt_f32_ubyte2_e32 v242, v146
	v_cvt_f32_ubyte3_e32 v243, v146
	v_cvt_f32_ubyte0_e32 v244, v147
	v_cvt_f32_ubyte1_e32 v245, v147
	v_cvt_f32_ubyte2_e32 v246, v147
	v_cvt_f32_ubyte3_e32 v247, v147
	v_cvt_f32_ubyte0_e32 v248, v222
	v_cvt_f32_ubyte1_e32 v249, v222
	v_cvt_f32_ubyte2_e32 v250, v222
	v_cvt_f32_ubyte3_e32 v251, v222
	v_cvt_f32_ubyte0_e32 v252, v223
	v_cvt_f32_ubyte1_e32 v253, v223
	v_cvt_f32_ubyte2_e32 v254, v223
	v_cvt_f32_ubyte3_e32 v255, v223
	v_rcp_iflag_f32_e32 v248, v248
	v_rcp_iflag_f32_e32 v249, v249
	v_rcp_iflag_f32_e32 v250, v250
	v_rcp_iflag_f32_e32 v251, v251
	v_rcp_iflag_f32_e32 v252, v252
	v_rcp_iflag_f32_e32 v253, v253
	v_rcp_iflag_f32_e32 v254, v254
	v_rcp_iflag_f32_e32 v255, v255
	v_pk_mul_f32 v[240:241], v[248:249], v[240:241]
	v_pk_mul_f32 v[242:243], v[250:251], v[242:243]
	v_pk_mul_f32 v[244:245], v[252:253], v[244:245]
	v_pk_mul_f32 v[246:247], v[254:255], v[246:247]
	v_pk_mul_f32 v[84:85], v[84:85], v[240:241]
	v_pk_mul_f32 v[86:87], v[86:87], v[242:243]
	v_pk_mul_f32 v[80:81], v[80:81], v[244:245]
	v_pk_mul_f32 v[82:83], v[82:83], v[246:247]
	s_waitcnt vmcnt(8)
	v_cvt_f32_ubyte0_e32 v240, v148
	v_cvt_f32_ubyte1_e32 v241, v148
	v_cvt_f32_ubyte2_e32 v242, v148
	v_cvt_f32_ubyte3_e32 v243, v148
	v_cvt_f32_ubyte0_e32 v244, v149
	v_cvt_f32_ubyte1_e32 v245, v149
	v_cvt_f32_ubyte2_e32 v246, v149
	v_cvt_f32_ubyte3_e32 v247, v149
	v_cvt_f32_ubyte0_e32 v248, v224
	v_cvt_f32_ubyte1_e32 v249, v224
	v_cvt_f32_ubyte2_e32 v250, v224
	v_cvt_f32_ubyte3_e32 v251, v224
	v_cvt_f32_ubyte0_e32 v252, v225
	v_cvt_f32_ubyte1_e32 v253, v225
	v_cvt_f32_ubyte2_e32 v254, v225
	v_cvt_f32_ubyte3_e32 v255, v225
	v_rcp_iflag_f32_e32 v248, v248
	v_rcp_iflag_f32_e32 v249, v249
	v_rcp_iflag_f32_e32 v250, v250
	v_rcp_iflag_f32_e32 v251, v251
	v_rcp_iflag_f32_e32 v252, v252
	v_rcp_iflag_f32_e32 v253, v253
	v_rcp_iflag_f32_e32 v254, v254
	v_rcp_iflag_f32_e32 v255, v255
	v_pk_mul_f32 v[240:241], v[248:249], v[240:241]
	v_pk_mul_f32 v[242:243], v[250:251], v[242:243]
	v_pk_mul_f32 v[244:245], v[252:253], v[244:245]
	v_pk_mul_f32 v[246:247], v[254:255], v[246:247]
	v_pk_mul_f32 v[116:117], v[116:117], v[240:241]
	v_pk_mul_f32 v[118:119], v[118:119], v[242:243]
	v_pk_mul_f32 v[112:113], v[112:113], v[244:245]
	v_pk_mul_f32 v[114:115], v[114:115], v[246:247]
	v_cvt_f32_ubyte0_e32 v240, v150
	v_cvt_f32_ubyte1_e32 v241, v150
	v_cvt_f32_ubyte2_e32 v242, v150
	v_cvt_f32_ubyte3_e32 v243, v150
	v_cvt_f32_ubyte0_e32 v244, v151
	v_cvt_f32_ubyte1_e32 v245, v151
	v_cvt_f32_ubyte2_e32 v246, v151
	v_cvt_f32_ubyte3_e32 v247, v151
	v_cvt_f32_ubyte0_e32 v248, v226
	v_cvt_f32_ubyte1_e32 v249, v226
	v_cvt_f32_ubyte2_e32 v250, v226
	v_cvt_f32_ubyte3_e32 v251, v226
	v_cvt_f32_ubyte0_e32 v252, v227
	v_cvt_f32_ubyte1_e32 v253, v227
	v_cvt_f32_ubyte2_e32 v254, v227
	v_cvt_f32_ubyte3_e32 v255, v227
	v_rcp_iflag_f32_e32 v248, v248
	v_rcp_iflag_f32_e32 v249, v249
	v_rcp_iflag_f32_e32 v250, v250
	v_rcp_iflag_f32_e32 v251, v251
	v_rcp_iflag_f32_e32 v252, v252
	v_rcp_iflag_f32_e32 v253, v253
	v_rcp_iflag_f32_e32 v254, v254
	v_rcp_iflag_f32_e32 v255, v255
	v_pk_mul_f32 v[240:241], v[248:249], v[240:241]
	v_pk_mul_f32 v[242:243], v[250:251], v[242:243]
	v_pk_mul_f32 v[244:245], v[252:253], v[244:245]
	v_pk_mul_f32 v[246:247], v[254:255], v[246:247]
	v_pk_mul_f32 v[76:77], v[76:77], v[240:241]
	v_pk_mul_f32 v[78:79], v[78:79], v[242:243]
	v_pk_mul_f32 v[72:73], v[72:73], v[244:245]
	v_pk_mul_f32 v[74:75], v[74:75], v[246:247]
	s_waitcnt vmcnt(6)
;     template <int KIND> __device__ __forceinline__ void run(f32x4 (&acc)[2][2][4][2], const Unit& u, int tid_in) const {
;     ...
;                             const f32x4 n0 = unpack4_raw(bj == 0 ? qa[ml].x : qa[ml].z), n1 = unpack4_raw(bj == 0 ? qa[ml].y : qa[ml].w);
;                             if (r < 2) { const f32x4 d0 = unpack4_raw(bj == 0 ? qb[ml].x : qb[ml].z), d1 = unpack4_raw(bj == 0 ? qb[ml].y : qb[ml].w);
; #pragma unroll
;                                 for (int j = 0; j < 4; ++j) { acc[ai][bj][m][0][j] *= n0[j] * __builtin_amdgcn_rcpf(d0[j]); acc[ai][bj][m][1][j] *= n1[j] * __builtin_amdgcn_rcpf(d1[j]); } }
	v_cvt_f32_ubyte0_e32 v240, v196
	v_cvt_f32_ubyte1_e32 v241, v196
	v_cvt_f32_ubyte2_e32 v242, v196
	v_cvt_f32_ubyte3_e32 v243, v196
	v_cvt_f32_ubyte0_e32 v244, v197
	v_cvt_f32_ubyte1_e32 v245, v197
	v_cvt_f32_ubyte2_e32 v246, v197
	v_cvt_f32_ubyte3_e32 v247, v197
	v_cvt_f32_ubyte0_e32 v248, v178
	v_cvt_f32_ubyte1_e32 v249, v178
	v_cvt_f32_ubyte2_e32 v250, v178
	v_cvt_f32_ubyte3_e32 v251, v178
	v_cvt_f32_ubyte0_e32 v252, v179
	v_cvt_f32_ubyte1_e32 v253, v179
	v_cvt_f32_ubyte2_e32 v254, v179
	v_cvt_f32_ubyte3_e32 v255, v179
	v_rcp_iflag_f32_e32 v248, v248
	v_rcp_iflag_f32_e32 v249, v249
	v_rcp_iflag_f32_e32 v250, v250
	v_rcp_iflag_f32_e32 v251, v251
	v_rcp_iflag_f32_e32 v252, v252
	v_rcp_iflag_f32_e32 v253, v253
	v_rcp_iflag_f32_e32 v254, v254
	v_rcp_iflag_f32_e32 v255, v255
	v_pk_mul_f32 v[240:241], v[248:249], v[240:241]
	v_pk_mul_f32 v[242:243], v[250:251], v[242:243]
	v_pk_mul_f32 v[244:245], v[252:253], v[244:245]
	v_pk_mul_f32 v[246:247], v[254:255], v[246:247]
	v_pk_mul_f32 v[68:69], v[68:69], v[240:241]
	v_pk_mul_f32 v[70:71], v[70:71], v[242:243]
	v_pk_mul_f32 v[64:65], v[64:65], v[244:245]
	v_pk_mul_f32 v[66:67], v[66:67], v[246:247]
	v_cvt_f32_ubyte0_e32 v240, v198
	v_cvt_f32_ubyte1_e32 v241, v198
	v_cvt_f32_ubyte2_e32 v242, v198
	v_cvt_f32_ubyte3_e32 v243, v198
	v_cvt_f32_ubyte0_e32 v244, v199
	v_cvt_f32_ubyte1_e32 v245, v199
	v_cvt_f32_ubyte2_e32 v246, v199
	v_cvt_f32_ubyte3_e32 v247, v199
	v_cvt_f32_ubyte0_e32 v248, v180
	v_cvt_f32_ubyte1_e32 v249, v180
	v_cvt_f32_ubyte2_e32 v250, v180
	v_cvt_f32_ubyte3_e32 v251, v180
	v_cvt_f32_ubyte0_e32 v252, v181
	v_cvt_f32_ubyte1_e32 v253, v181
	v_cvt_f32_ubyte2_e32 v254, v181
	v_cvt_f32_ubyte3_e32 v255, v181
	v_rcp_iflag_f32_e32 v248, v248
	v_rcp_iflag_f32_e32 v249, v249
	v_rcp_iflag_f32_e32 v250, v250
	v_rcp_iflag_f32_e32 v251, v251
	v_rcp_iflag_f32_e32 v252, v252
	v_rcp_iflag_f32_e32 v253, v253
	v_rcp_iflag_f32_e32 v254, v254
	v_rcp_iflag_f32_e32 v255, v255
	v_pk_mul_f32 v[240:241], v[248:249], v[240:241]
	v_pk_mul_f32 v[242:243], v[250:251], v[242:243]
	v_pk_mul_f32 v[244:245], v[252:253], v[244:245]
	v_pk_mul_f32 v[246:247], v[254:255], v[246:247]
	v_pk_mul_f32 v[36:37], v[36:37], v[240:241]
	v_pk_mul_f32 v[38:39], v[38:39], v[242:243]
	v_pk_mul_f32 v[32:33], v[32:33], v[244:245]
	v_pk_mul_f32 v[34:35], v[34:35], v[246:247]
	s_waitcnt vmcnt(4)
	v_cvt_f32_ubyte0_e32 v240, v200
	v_cvt_f32_ubyte1_e32 v241, v200
	v_cvt_f32_ubyte2_e32 v242, v200
	v_cvt_f32_ubyte3_e32 v243, v200
	v_cvt_f32_ubyte0_e32 v244, v201
	v_cvt_f32_ubyte1_e32 v245, v201
	v_cvt_f32_ubyte2_e32 v246, v201
	v_cvt_f32_ubyte3_e32 v247, v201
	v_cvt_f32_ubyte0_e32 v248, v182
	v_cvt_f32_ubyte1_e32 v249, v182
	v_cvt_f32_ubyte2_e32 v250, v182
	v_cvt_f32_ubyte3_e32 v251, v182
	v_cvt_f32_ubyte0_e32 v252, v183
	v_cvt_f32_ubyte1_e32 v253, v183
	v_cvt_f32_ubyte2_e32 v254, v183
	v_cvt_f32_ubyte3_e32 v255, v183
	v_rcp_iflag_f32_e32 v248, v248
	v_rcp_iflag_f32_e32 v249, v249
	v_rcp_iflag_f32_e32 v250, v250
	v_rcp_iflag_f32_e32 v251, v251
	v_rcp_iflag_f32_e32 v252, v252
	v_rcp_iflag_f32_e32 v253, v253
	v_rcp_iflag_f32_e32 v254, v254
	v_rcp_iflag_f32_e32 v255, v255
	v_pk_mul_f32 v[240:241], v[248:249], v[240:241]
	v_pk_mul_f32 v[242:243], v[250:251], v[242:243]
	v_pk_mul_f32 v[244:245], v[252:253], v[244:245]
	v_pk_mul_f32 v[246:247], v[254:255], v[246:247]
	v_pk_mul_f32 v[60:61], v[60:61], v[240:241]
	v_pk_mul_f32 v[62:63], v[62:63], v[242:243]
	v_pk_mul_f32 v[56:57], v[56:57], v[244:245]
	v_pk_mul_f32 v[58:59], v[58:59], v[246:247]
	v_cvt_f32_ubyte0_e32 v240, v202
	v_cvt_f32_ubyte1_e32 v241, v202
	v_cvt_f32_ubyte2_e32 v242, v202
	v_cvt_f32_ubyte3_e32 v243, v202
	v_cvt_f32_ubyte0_e32 v244, v203
	v_cvt_f32_ubyte1_e32 v245, v203
	v_cvt_f32_ubyte2_e32 v246, v203
	v_cvt_f32_ubyte3_e32 v247, v203
	v_cvt_f32_ubyte0_e32 v248, v184
	v_cvt_f32_ubyte1_e32 v249, v184
	v_cvt_f32_ubyte2_e32 v250, v184
	v_cvt_f32_ubyte3_e32 v251, v184
	v_cvt_f32_ubyte0_e32 v252, v185
	v_cvt_f32_ubyte1_e32 v253, v185
	v_cvt_f32_ubyte2_e32 v254, v185
	v_cvt_f32_ubyte3_e32 v255, v185
	v_rcp_iflag_f32_e32 v248, v248
	v_rcp_iflag_f32_e32 v249, v249
	v_rcp_iflag_f32_e32 v250, v250
	v_rcp_iflag_f32_e32 v251, v251
	v_rcp_iflag_f32_e32 v252, v252
	v_rcp_iflag_f32_e32 v253, v253
	v_rcp_iflag_f32_e32 v254, v254
	v_rcp_iflag_f32_e32 v255, v255
	v_pk_mul_f32 v[240:241], v[248:249], v[240:241]
	v_pk_mul_f32 v[242:243], v[250:251], v[242:243]
	v_pk_mul_f32 v[244:245], v[252:253], v[244:245]
	v_pk_mul_f32 v[246:247], v[254:255], v[246:247]
	v_pk_mul_f32 v[28:29], v[28:29], v[240:241]
	v_pk_mul_f32 v[30:31], v[30:31], v[242:243]
	v_pk_mul_f32 v[24:25], v[24:25], v[244:245]
	v_pk_mul_f32 v[26:27], v[26:27], v[246:247]
	s_waitcnt vmcnt(2)
;     template <int KIND> __device__ __forceinline__ void run(f32x4 (&acc)[2][2][4][2], const Unit& u, int tid_in) const {
;     ...
;                             const f32x4 n0 = unpack4_raw(bj == 0 ? qa[ml].x : qa[ml].z), n1 = unpack4_raw(bj == 0 ? qa[ml].y : qa[ml].w);
;                             if (r < 2) { const f32x4 d0 = unpack4_raw(bj == 0 ? qb[ml].x : qb[ml].z), d1 = unpack4_raw(bj == 0 ? qb[ml].y : qb[ml].w);
; #pragma unroll
;                                 for (int j = 0; j < 4; ++j) { acc[ai][bj][m][0][j] *= n0[j] * __builtin_amdgcn_rcpf(d0[j]); acc[ai][bj][m][1][j] *= n1[j] * __builtin_amdgcn_rcpf(d1[j]); } }
	v_cvt_f32_ubyte0_e32 v240, v204
	v_cvt_f32_ubyte1_e32 v241, v204
	v_cvt_f32_ubyte2_e32 v242, v204
	v_cvt_f32_ubyte3_e32 v243, v204
	v_cvt_f32_ubyte0_e32 v244, v205
	v_cvt_f32_ubyte1_e32 v245, v205
	v_cvt_f32_ubyte2_e32 v246, v205
	v_cvt_f32_ubyte3_e32 v247, v205
	v_cvt_f32_ubyte0_e32 v248, v158
	v_cvt_f32_ubyte1_e32 v249, v158
	v_cvt_f32_ubyte2_e32 v250, v158
	v_cvt_f32_ubyte3_e32 v251, v158
	v_cvt_f32_ubyte0_e32 v252, v159
	v_cvt_f32_ubyte1_e32 v253, v159
	v_cvt_f32_ubyte2_e32 v254, v159
	v_cvt_f32_ubyte3_e32 v255, v159
	v_rcp_iflag_f32_e32 v248, v248
	v_rcp_iflag_f32_e32 v249, v249
	v_rcp_iflag_f32_e32 v250, v250
	v_rcp_iflag_f32_e32 v251, v251
	v_rcp_iflag_f32_e32 v252, v252
	v_rcp_iflag_f32_e32 v253, v253
	v_rcp_iflag_f32_e32 v254, v254
	v_rcp_iflag_f32_e32 v255, v255
	v_pk_mul_f32 v[240:241], v[248:249], v[240:241]
	v_pk_mul_f32 v[242:243], v[250:251], v[242:243]
	v_pk_mul_f32 v[244:245], v[252:253], v[244:245]
	v_pk_mul_f32 v[246:247], v[254:255], v[246:247]
	v_pk_mul_f32 v[52:53], v[52:53], v[240:241]
	v_pk_mul_f32 v[54:55], v[54:55], v[242:243]
	v_pk_mul_f32 v[48:49], v[48:49], v[244:245]
	v_pk_mul_f32 v[50:51], v[50:51], v[246:247]
	v_cvt_f32_ubyte0_e32 v240, v206
	v_cvt_f32_ubyte1_e32 v241, v206
	v_cvt_f32_ubyte2_e32 v242, v206
	v_cvt_f32_ubyte3_e32 v243, v206
	v_cvt_f32_ubyte0_e32 v244, v207
	v_cvt_f32_ubyte1_e32 v245, v207
	v_cvt_f32_ubyte2_e32 v246, v207
	v_cvt_f32_ubyte3_e32 v247, v207
	v_cvt_f32_ubyte0_e32 v248, v160
	v_cvt_f32_ubyte1_e32 v249, v160
	v_cvt_f32_ubyte2_e32 v250, v160
	v_cvt_f32_ubyte3_e32 v251, v160
	v_cvt_f32_ubyte0_e32 v252, v161
	v_cvt_f32_ubyte1_e32 v253, v161
	v_cvt_f32_ubyte2_e32 v254, v161
	v_cvt_f32_ubyte3_e32 v255, v161
	v_rcp_iflag_f32_e32 v248, v248
	v_rcp_iflag_f32_e32 v249, v249
	v_rcp_iflag_f32_e32 v250, v250
	v_rcp_iflag_f32_e32 v251, v251
	v_rcp_iflag_f32_e32 v252, v252
	v_rcp_iflag_f32_e32 v253, v253
	v_rcp_iflag_f32_e32 v254, v254
	v_rcp_iflag_f32_e32 v255, v255
	v_pk_mul_f32 v[240:241], v[248:249], v[240:241]
	v_pk_mul_f32 v[242:243], v[250:251], v[242:243]
	v_pk_mul_f32 v[244:245], v[252:253], v[244:245]
	v_pk_mul_f32 v[246:247], v[254:255], v[246:247]
	v_pk_mul_f32 v[20:21], v[20:21], v[240:241]
	v_pk_mul_f32 v[22:23], v[22:23], v[242:243]
	v_pk_mul_f32 v[16:17], v[16:17], v[244:245]
	v_pk_mul_f32 v[18:19], v[18:19], v[246:247]
	s_waitcnt vmcnt(0)
	v_cvt_f32_ubyte0_e32 v240, v208
	v_cvt_f32_ubyte1_e32 v241, v208
	v_cvt_f32_ubyte2_e32 v242, v208
	v_cvt_f32_ubyte3_e32 v243, v208
	v_cvt_f32_ubyte0_e32 v244, v209
	v_cvt_f32_ubyte1_e32 v245, v209
	v_cvt_f32_ubyte2_e32 v246, v209
	v_cvt_f32_ubyte3_e32 v247, v209
	v_cvt_f32_ubyte0_e32 v248, v162
	v_cvt_f32_ubyte1_e32 v249, v162
	v_cvt_f32_ubyte2_e32 v250, v162
	v_cvt_f32_ubyte3_e32 v251, v162
	v_cvt_f32_ubyte0_e32 v252, v163
	v_cvt_f32_ubyte1_e32 v253, v163
	v_cvt_f32_ubyte2_e32 v254, v163
	v_cvt_f32_ubyte3_e32 v255, v163
	v_rcp_iflag_f32_e32 v248, v248
	v_rcp_iflag_f32_e32 v249, v249
	v_rcp_iflag_f32_e32 v250, v250
	v_rcp_iflag_f32_e32 v251, v251
	v_rcp_iflag_f32_e32 v252, v252
	v_rcp_iflag_f32_e32 v253, v253
	v_rcp_iflag_f32_e32 v254, v254
	v_rcp_iflag_f32_e32 v255, v255
	v_pk_mul_f32 v[240:241], v[248:249], v[240:241]
	v_pk_mul_f32 v[242:243], v[250:251], v[242:243]
	v_pk_mul_f32 v[244:245], v[252:253], v[244:245]
	v_pk_mul_f32 v[246:247], v[254:255], v[246:247]
	v_pk_mul_f32 v[44:45], v[44:45], v[240:241]
	v_pk_mul_f32 v[46:47], v[46:47], v[242:243]
	v_pk_mul_f32 v[40:41], v[40:41], v[244:245]
	v_pk_mul_f32 v[42:43], v[42:43], v[246:247]
	v_cvt_f32_ubyte0_e32 v240, v210
	v_cvt_f32_ubyte1_e32 v241, v210
	v_cvt_f32_ubyte2_e32 v242, v210
	v_cvt_f32_ubyte3_e32 v243, v210
	v_cvt_f32_ubyte0_e32 v244, v211
	v_cvt_f32_ubyte1_e32 v245, v211
	v_cvt_f32_ubyte2_e32 v246, v211
	v_cvt_f32_ubyte3_e32 v247, v211
	v_cvt_f32_ubyte0_e32 v248, v164
	v_cvt_f32_ubyte1_e32 v249, v164
	v_cvt_f32_ubyte2_e32 v250, v164
	v_cvt_f32_ubyte3_e32 v251, v164
	v_cvt_f32_ubyte0_e32 v252, v165
	v_cvt_f32_ubyte1_e32 v253, v165
	v_cvt_f32_ubyte2_e32 v254, v165
	v_cvt_f32_ubyte3_e32 v255, v165
	v_rcp_iflag_f32_e32 v248, v248
	v_rcp_iflag_f32_e32 v249, v249
	v_rcp_iflag_f32_e32 v250, v250
	v_rcp_iflag_f32_e32 v251, v251
	v_rcp_iflag_f32_e32 v252, v252
	v_rcp_iflag_f32_e32 v253, v253
	v_rcp_iflag_f32_e32 v254, v254
	v_rcp_iflag_f32_e32 v255, v255
	v_pk_mul_f32 v[240:241], v[248:249], v[240:241]
	v_pk_mul_f32 v[242:243], v[250:251], v[242:243]
	v_pk_mul_f32 v[244:245], v[252:253], v[244:245]
	v_pk_mul_f32 v[246:247], v[254:255], v[246:247]
	v_pk_mul_f32 v[12:13], v[12:13], v[240:241]
	v_pk_mul_f32 v[14:15], v[14:15], v[242:243]
	v_pk_mul_f32 v[8:9], v[8:9], v[244:245]
	v_pk_mul_f32 v[10:11], v[10:11], v[246:247]
	s_mov_b64 s[6:7], -1
	s_branch .Lmg1_done
; __device__ __forceinline__ u32x4 pack8(const f32x4 a, const f32x4 b) { u32x4 w; w.x = cvt_pk_bf16(a[0], a[1]); w.y = cvt_pk_bf16(a[2], a[3]); w.z = cvt_pk_bf16(b[0], b[1]); w.w = cvt_pk_bf16(b[2], b[3]); return w; }
;     template <int KIND> __device__ __forceinline__ void run(f32x4 (&acc)[2][2][4][2], const Unit& u, int tid_in) const {
;     ...
;                     for (int ml = 0; ml < 2; ++ml) { const int m = mh * 2 + ml; qa[ml] = gst[(size_t)r * 4096 + (ai * 4 + m) * 512 + tid]; qb[ml] = (r < 2) ? gst[(size_t)(r + 1) * 4096 + (ai * 4 + m) * 512 + tid] : qa[ml]; }
; #pragma unroll
;                     for (int ml = 0; ml < 2; ++ml) { const int m = mh * 2 + ml; int row = rbase + ai * 128 + m * 16; asm volatile("" : "+v"(row));
; #pragma unroll
;                         for (int bj = 0; bj < 2; ++bj) {
;                             const f32x4 n0 = unpack4_raw(bj == 0 ? qa[ml].x : qa[ml].z), n1 = unpack4_raw(bj == 0 ? qa[ml].y : qa[ml].w);
;                             if (r < 2) { const f32x4 d0 = unpack4_raw(bj == 0 ? qb[ml].x : qb[ml].z), d1 = unpack4_raw(bj == 0 ? qb[ml].y : qb[ml].w);
; #pragma unroll
;                                 for (int j = 0; j < 4; ++j) { acc[ai][bj][m][0][j] *= n0[j] * __builtin_amdgcn_rcpf(d0[j]); acc[ai][bj][m][1][j] *= n1[j] * __builtin_amdgcn_rcpf(d1[j]); } }
;                             else { const f32x4 o0 = acc[ai][bj][m][0] * n0 * (1.0f / 255.0f), o1 = acc[ai][bj][m][1] * n1 * (1.0f / 255.0f);
;                                 *(u32x4*)(mg + (size_t)row * 1024 + u.pn * 256 + bj * 128 + cl) = pack8(o0, o1); } } }
.Lmg1_r2:
	global_load_dwordx4 v[136:139], v166, s[4:5]
	s_add_u32 s4, s4, 0x2000
	s_addc_u32 s5, s5, 0
	global_load_dwordx4 v[140:143], v166, s[4:5]
	s_add_u32 s4, s4, 0x2000
	s_addc_u32 s5, s5, 0
	global_load_dwordx4 v[144:147], v166, s[4:5]
	s_add_u32 s4, s4, 0x2000
	s_addc_u32 s5, s5, 0
	global_load_dwordx4 v[148:151], v166, s[4:5]
	s_add_u32 s4, s4, 0x2000
	s_addc_u32 s5, s5, 0
	global_load_dwordx4 v[196:199], v166, s[4:5]
	s_add_u32 s4, s4, 0x2000
	s_addc_u32 s5, s5, 0
	global_load_dwordx4 v[200:203], v166, s[4:5]
	s_add_u32 s4, s4, 0x2000
	s_addc_u32 s5, s5, 0
	global_load_dwordx4 v[204:207], v166, s[4:5]
	s_add_u32 s4, s4, 0x2000
	s_addc_u32 s5, s5, 0
	global_load_dwordx4 v[208:211], v166, s[4:5]
	v_readfirstlane_b32 s18, v174
	s_ashr_i32 s8, s18, 2
	s_andn2_b32 s8, s8, 63
	v_and_or_b32 v167, v174, 15, s8
	v_lshl_add_u32 v167, s33, 8, v167
	s_lshr_b32 s9, s18, 1
	s_and_b32 s9, s9, 0x60
	v_lshrrev_b32_e32 v172, 1, v174
	v_and_or_b32 v172, v172, 24, s9
	v_lshlrev_b32_e32 v172, 1, v172
	v_lshlrev_b32_e32 v167, 11, v167
	s_lshl_b32 s8, s40, 9
	v_add3_u32 v167, v167, v172, s8
	s_mov_b64 s[8:9], s[10:11]
	s_mov_b32 s2, 0x3b808081
	s_waitcnt vmcnt(7)
	v_cvt_f32_ubyte0_e32 v240, v136
	v_cvt_f32_ubyte1_e32 v241, v136
	v_cvt_f32_ubyte2_e32 v242, v136
	v_cvt_f32_ubyte3_e32 v243, v136
	v_cvt_f32_ubyte0_e32 v244, v137
	v_cvt_f32_ubyte1_e32 v245, v137
	v_cvt_f32_ubyte2_e32 v246, v137
	v_cvt_f32_ubyte3_e32 v247, v137
	v_pk_mul_f32 v[248:249], v[104:105], v[240:241]
	v_pk_mul_f32 v[250:251], v[106:107], v[242:243]
	v_pk_mul_f32 v[252:253], v[108:109], v[244:245]
	v_pk_mul_f32 v[254:255], v[110:111], v[246:247]
	v_pk_mul_f32 v[248:249], v[248:249], s[2:3] op_sel_hi:[1,0]
	v_pk_mul_f32 v[250:251], v[250:251], s[2:3] op_sel_hi:[1,0]
	v_pk_mul_f32 v[252:253], v[252:253], s[2:3] op_sel_hi:[1,0]
	v_pk_mul_f32 v[254:255], v[254:255], s[2:3] op_sel_hi:[1,0]
	v_cvt_pk_bf16_f32 v234, v248, v249
	v_cvt_pk_bf16_f32 v235, v250, v251
	v_cvt_pk_bf16_f32 v236, v252, v253
	v_cvt_pk_bf16_f32 v237, v254, v255
	global_store_dwordx4 v167, v[234:237], s[8:9]
	v_cvt_f32_ubyte0_e32 v240, v138
	v_cvt_f32_ubyte1_e32 v241, v138
	v_cvt_f32_ubyte2_e32 v242, v138
	v_cvt_f32_ubyte3_e32 v243, v138
	v_cvt_f32_ubyte0_e32 v244, v139
	v_cvt_f32_ubyte1_e32 v245, v139
	v_cvt_f32_ubyte2_e32 v246, v139
	v_cvt_f32_ubyte3_e32 v247, v139
	v_pk_mul_f32 v[248:249], v[100:101], v[240:241]
	v_pk_mul_f32 v[250:251], v[102:103], v[242:243]
	v_pk_mul_f32 v[252:253], v[96:97], v[244:245]
	v_pk_mul_f32 v[254:255], v[98:99], v[246:247]
	v_pk_mul_f32 v[248:249], v[248:249], s[2:3] op_sel_hi:[1,0]
	v_pk_mul_f32 v[250:251], v[250:251], s[2:3] op_sel_hi:[1,0]
	v_pk_mul_f32 v[252:253], v[252:253], s[2:3] op_sel_hi:[1,0]
	v_pk_mul_f32 v[254:255], v[254:255], s[2:3] op_sel_hi:[1,0]
	v_cvt_pk_bf16_f32 v234, v248, v249
	v_cvt_pk_bf16_f32 v235, v250, v251
	v_cvt_pk_bf16_f32 v236, v252, v253
	v_cvt_pk_bf16_f32 v237, v254, v255
	global_store_dwordx4 v167, v[234:237], s[8:9] offset:256
	s_add_u32 s8, s8, 0x8000
	s_addc_u32 s9, s9, 0
	s_waitcnt vmcnt(8)
	v_cvt_f32_ubyte0_e32 v240, v140
	v_cvt_f32_ubyte1_e32 v241, v140
	v_cvt_f32_ubyte2_e32 v242, v140
	v_cvt_f32_ubyte3_e32 v243, v140
	v_cvt_f32_ubyte0_e32 v244, v141
	v_cvt_f32_ubyte1_e32 v245, v141
	v_cvt_f32_ubyte2_e32 v246, v141
	v_cvt_f32_ubyte3_e32 v247, v141
	v_pk_mul_f32 v[248:249], v[132:133], v[240:241]
	v_pk_mul_f32 v[250:251], v[134:135], v[242:243]
	v_pk_mul_f32 v[252:253], v[128:129], v[244:245]
	v_pk_mul_f32 v[254:255], v[130:131], v[246:247]
	v_pk_mul_f32 v[248:249], v[248:249], s[2:3] op_sel_hi:[1,0]
	v_pk_mul_f32 v[250:251], v[250:251], s[2:3] op_sel_hi:[1,0]
	v_pk_mul_f32 v[252:253], v[252:253], s[2:3] op_sel_hi:[1,0]
	v_pk_mul_f32 v[254:255], v[254:255], s[2:3] op_sel_hi:[1,0]
	v_cvt_pk_bf16_f32 v234, v248, v249
	v_cvt_pk_bf16_f32 v235, v250, v251
	v_cvt_pk_bf16_f32 v236, v252, v253
	v_cvt_pk_bf16_f32 v237, v254, v255
	global_store_dwordx4 v167, v[234:237], s[8:9]
	v_cvt_f32_ubyte0_e32 v240, v142
	v_cvt_f32_ubyte1_e32 v241, v142
	v_cvt_f32_ubyte2_e32 v242, v142
	v_cvt_f32_ubyte3_e32 v243, v142
	v_cvt_f32_ubyte0_e32 v244, v143
	v_cvt_f32_ubyte1_e32 v245, v143
	v_cvt_f32_ubyte2_e32 v246, v143
	v_cvt_f32_ubyte3_e32 v247, v143
	v_pk_mul_f32 v[248:249], v[92:93], v[240:241]
	v_pk_mul_f32 v[250:251], v[94:95], v[242:243]
	v_pk_mul_f32 v[252:253], v[88:89], v[244:245]
	v_pk_mul_f32 v[254:255], v[90:91], v[246:247]
	v_pk_mul_f32 v[248:249], v[248:249], s[2:3] op_sel_hi:[1,0]
	v_pk_mul_f32 v[250:251], v[250:251], s[2:3] op_sel_hi:[1,0]
	v_pk_mul_f32 v[252:253], v[252:253], s[2:3] op_sel_hi:[1,0]
	v_pk_mul_f32 v[254:255], v[254:255], s[2:3] op_sel_hi:[1,0]
	v_cvt_pk_bf16_f32 v234, v248, v249
	v_cvt_pk_bf16_f32 v235, v250, v251
	v_cvt_pk_bf16_f32 v236, v252, v253
	v_cvt_pk_bf16_f32 v237, v254, v255
	global_store_dwordx4 v167, v[234:237], s[8:9] offset:256
	s_add_u32 s8, s8, 0x8000
	s_addc_u32 s9, s9, 0
	s_waitcnt vmcnt(9)
; __device__ __forceinline__ u32x4 pack8(const f32x4 a, const f32x4 b) { u32x4 w; w.x = cvt_pk_bf16(a[0], a[1]); w.y = cvt_pk_bf16(a[2], a[3]); w.z = cvt_pk_bf16(b[0], b[1]); w.w = cvt_pk_bf16(b[2], b[3]); return w; }
;     template <int KIND> __device__ __forceinline__ void run(f32x4 (&acc)[2][2][4][2], const Unit& u, int tid_in) const {
;     ...
;                             const f32x4 n0 = unpack4_raw(bj == 0 ? qa[ml].x : qa[ml].z), n1 = unpack4_raw(bj == 0 ? qa[ml].y : qa[ml].w);
;                             if (r < 2) { const f32x4 d0 = unpack4_raw(bj == 0 ? qb[ml].x : qb[ml].z), d1 = unpack4_raw(bj == 0 ? qb[ml].y : qb[ml].w);
; #pragma unroll
;                                 for (int j = 0; j < 4; ++j) { acc[ai][bj][m][0][j] *= n0[j] * __builtin_amdgcn_rcpf(d0[j]); acc[ai][bj][m][1][j] *= n1[j] * __builtin_amdgcn_rcpf(d1[j]); } }
;                             else { const f32x4 o0 = acc[ai][bj][m][0] * n0 * (1.0f / 255.0f), o1 = acc[ai][bj][m][1] * n1 * (1.0f / 255.0f);
;                                 *(u32x4*)(mg + (size_t)row * 1024 + u.pn * 256 + bj * 128 + cl) = pack8(o0, o1); } } }
	v_cvt_f32_ubyte0_e32 v240, v144
	v_cvt_f32_ubyte1_e32 v241, v144
	v_cvt_f32_ubyte2_e32 v242, v144
	v_cvt_f32_ubyte3_e32 v243, v144
	v_cvt_f32_ubyte0_e32 v244, v145
	v_cvt_f32_ubyte1_e32 v245, v145
	v_cvt_f32_ubyte2_e32 v246, v145
	v_cvt_f32_ubyte3_e32 v247, v145
	v_pk_mul_f32 v[248:249], v[124:125], v[240:241]
	v_pk_mul_f32 v[250:251], v[126:127], v[242:243]
	v_pk_mul_f32 v[252:253], v[120:121], v[244:245]
	v_pk_mul_f32 v[254:255], v[122:123], v[246:247]
	v_pk_mul_f32 v[248:249], v[248:249], s[2:3] op_sel_hi:[1,0]
	v_pk_mul_f32 v[250:251], v[250:251], s[2:3] op_sel_hi:[1,0]
	v_pk_mul_f32 v[252:253], v[252:253], s[2:3] op_sel_hi:[1,0]
	v_pk_mul_f32 v[254:255], v[254:255], s[2:3] op_sel_hi:[1,0]
	v_cvt_pk_bf16_f32 v234, v248, v249
	v_cvt_pk_bf16_f32 v235, v250, v251
	v_cvt_pk_bf16_f32 v236, v252, v253
	v_cvt_pk_bf16_f32 v237, v254, v255
	global_store_dwordx4 v167, v[234:237], s[8:9]
	v_cvt_f32_ubyte0_e32 v240, v146
	v_cvt_f32_ubyte1_e32 v241, v146
	v_cvt_f32_ubyte2_e32 v242, v146
	v_cvt_f32_ubyte3_e32 v243, v146
	v_cvt_f32_ubyte0_e32 v244, v147
	v_cvt_f32_ubyte1_e32 v245, v147
	v_cvt_f32_ubyte2_e32 v246, v147
	v_cvt_f32_ubyte3_e32 v247, v147
	v_pk_mul_f32 v[248:249], v[84:85], v[240:241]
	v_pk_mul_f32 v[250:251], v[86:87], v[242:243]
	v_pk_mul_f32 v[252:253], v[80:81], v[244:245]
	v_pk_mul_f32 v[254:255], v[82:83], v[246:247]
	v_pk_mul_f32 v[248:249], v[248:249], s[2:3] op_sel_hi:[1,0]
	v_pk_mul_f32 v[250:251], v[250:251], s[2:3] op_sel_hi:[1,0]
	v_pk_mul_f32 v[252:253], v[252:253], s[2:3] op_sel_hi:[1,0]
	v_pk_mul_f32 v[254:255], v[254:255], s[2:3] op_sel_hi:[1,0]
	v_cvt_pk_bf16_f32 v234, v248, v249
	v_cvt_pk_bf16_f32 v235, v250, v251
	v_cvt_pk_bf16_f32 v236, v252, v253
	v_cvt_pk_bf16_f32 v237, v254, v255
	global_store_dwordx4 v167, v[234:237], s[8:9] offset:256
	s_add_u32 s8, s8, 0x8000
	s_addc_u32 s9, s9, 0
	s_waitcnt vmcnt(10)
	v_cvt_f32_ubyte0_e32 v240, v148
	v_cvt_f32_ubyte1_e32 v241, v148
	v_cvt_f32_ubyte2_e32 v242, v148
	v_cvt_f32_ubyte3_e32 v243, v148
	v_cvt_f32_ubyte0_e32 v244, v149
	v_cvt_f32_ubyte1_e32 v245, v149
	v_cvt_f32_ubyte2_e32 v246, v149
	v_cvt_f32_ubyte3_e32 v247, v149
	v_pk_mul_f32 v[248:249], v[116:117], v[240:241]
	v_pk_mul_f32 v[250:251], v[118:119], v[242:243]
	v_pk_mul_f32 v[252:253], v[112:113], v[244:245]
	v_pk_mul_f32 v[254:255], v[114:115], v[246:247]
	v_pk_mul_f32 v[248:249], v[248:249], s[2:3] op_sel_hi:[1,0]
	v_pk_mul_f32 v[250:251], v[250:251], s[2:3] op_sel_hi:[1,0]
	v_pk_mul_f32 v[252:253], v[252:253], s[2:3] op_sel_hi:[1,0]
	v_pk_mul_f32 v[254:255], v[254:255], s[2:3] op_sel_hi:[1,0]
	v_cvt_pk_bf16_f32 v234, v248, v249
	v_cvt_pk_bf16_f32 v235, v250, v251
	v_cvt_pk_bf16_f32 v236, v252, v253
	v_cvt_pk_bf16_f32 v237, v254, v255
	global_store_dwordx4 v167, v[234:237], s[8:9]
	v_cvt_f32_ubyte0_e32 v240, v150
	v_cvt_f32_ubyte1_e32 v241, v150
	v_cvt_f32_ubyte2_e32 v242, v150
	v_cvt_f32_ubyte3_e32 v243, v150
	v_cvt_f32_ubyte0_e32 v244, v151
	v_cvt_f32_ubyte1_e32 v245, v151
	v_cvt_f32_ubyte2_e32 v246, v151
	v_cvt_f32_ubyte3_e32 v247, v151
	v_pk_mul_f32 v[248:249], v[76:77], v[240:241]
	v_pk_mul_f32 v[250:251], v[78:79], v[242:243]
	v_pk_mul_f32 v[252:253], v[72:73], v[244:245]
	v_pk_mul_f32 v[254:255], v[74:75], v[246:247]
	v_pk_mul_f32 v[248:249], v[248:249], s[2:3] op_sel_hi:[1,0]
	v_pk_mul_f32 v[250:251], v[250:251], s[2:3] op_sel_hi:[1,0]
	v_pk_mul_f32 v[252:253], v[252:253], s[2:3] op_sel_hi:[1,0]
	v_pk_mul_f32 v[254:255], v[254:255], s[2:3] op_sel_hi:[1,0]
	v_cvt_pk_bf16_f32 v234, v248, v249
	v_cvt_pk_bf16_f32 v235, v250, v251
	v_cvt_pk_bf16_f32 v236, v252, v253
	v_cvt_pk_bf16_f32 v237, v254, v255
	global_store_dwordx4 v167, v[234:237], s[8:9] offset:256
	s_add_u32 s8, s8, 0x28000
	s_addc_u32 s9, s9, 0
	s_waitcnt vmcnt(11)
	v_cvt_f32_ubyte0_e32 v240, v196
	v_cvt_f32_ubyte1_e32 v241, v196
	v_cvt_f32_ubyte2_e32 v242, v196
	v_cvt_f32_ubyte3_e32 v243, v196
	v_cvt_f32_ubyte0_e32 v244, v197
	v_cvt_f32_ubyte1_e32 v245, v197
	v_cvt_f32_ubyte2_e32 v246, v197
	v_cvt_f32_ubyte3_e32 v247, v197
	v_pk_mul_f32 v[248:249], v[68:69], v[240:241]
	v_pk_mul_f32 v[250:251], v[70:71], v[242:243]
	v_pk_mul_f32 v[252:253], v[64:65], v[244:245]
	v_pk_mul_f32 v[254:255], v[66:67], v[246:247]
	v_pk_mul_f32 v[248:249], v[248:249], s[2:3] op_sel_hi:[1,0]
	v_pk_mul_f32 v[250:251], v[250:251], s[2:3] op_sel_hi:[1,0]
	v_pk_mul_f32 v[252:253], v[252:253], s[2:3] op_sel_hi:[1,0]
	v_pk_mul_f32 v[254:255], v[254:255], s[2:3] op_sel_hi:[1,0]
	v_cvt_pk_bf16_f32 v234, v248, v249
	v_cvt_pk_bf16_f32 v235, v250, v251
	v_cvt_pk_bf16_f32 v236, v252, v253
	v_cvt_pk_bf16_f32 v237, v254, v255
	global_store_dwordx4 v167, v[234:237], s[8:9]
	v_cvt_f32_ubyte0_e32 v240, v198
	v_cvt_f32_ubyte1_e32 v241, v198
	v_cvt_f32_ubyte2_e32 v242, v198
	v_cvt_f32_ubyte3_e32 v243, v198
	v_cvt_f32_ubyte0_e32 v244, v199
	v_cvt_f32_ubyte1_e32 v245, v199
	v_cvt_f32_ubyte2_e32 v246, v199
	v_cvt_f32_ubyte3_e32 v247, v199
	v_pk_mul_f32 v[248:249], v[36:37], v[240:241]
	v_pk_mul_f32 v[250:251], v[38:39], v[242:243]
	v_pk_mul_f32 v[252:253], v[32:33], v[244:245]
	v_pk_mul_f32 v[254:255], v[34:35], v[246:247]
	v_pk_mul_f32 v[248:249], v[248:249], s[2:3] op_sel_hi:[1,0]
	v_pk_mul_f32 v[250:251], v[250:251], s[2:3] op_sel_hi:[1,0]
	v_pk_mul_f32 v[252:253], v[252:253], s[2:3] op_sel_hi:[1,0]
	v_pk_mul_f32 v[254:255], v[254:255], s[2:3] op_sel_hi:[1,0]
	v_cvt_pk_bf16_f32 v234, v248, v249
	v_cvt_pk_bf16_f32 v235, v250, v251
	v_cvt_pk_bf16_f32 v236, v252, v253
	v_cvt_pk_bf16_f32 v237, v254, v255
	global_store_dwordx4 v167, v[234:237], s[8:9] offset:256
	s_add_u32 s8, s8, 0x8000
	s_addc_u32 s9, s9, 0
	s_waitcnt vmcnt(12)
; __device__ __forceinline__ u32x4 pack8(const f32x4 a, const f32x4 b) { u32x4 w; w.x = cvt_pk_bf16(a[0], a[1]); w.y = cvt_pk_bf16(a[2], a[3]); w.z = cvt_pk_bf16(b[0], b[1]); w.w = cvt_pk_bf16(b[2], b[3]); return w; }
; #define MEMFENCE asm volatile("" ::: "memory")
;     template <int KIND> __device__ __forceinline__ void run(f32x4 (&acc)[2][2][4][2], const Unit& u, int tid_in) const {
;     ...
;                     for (int ml = 0; ml < 2; ++ml) { const int m = mh * 2 + ml; qa[ml] = gst[(size_t)r * 4096 + (ai * 4 + m) * 512 + tid]; qb[ml] = (r < 2) ? gst[(size_t)(r + 1) * 4096 + (ai * 4 + m) * 512 + tid] : qa[ml]; }
; #pragma unroll
;                     for (int ml = 0; ml < 2; ++ml) { const int m = mh * 2 + ml; int row = rbase + ai * 128 + m * 16; asm volatile("" : "+v"(row));
; #pragma unroll
;                         for (int bj = 0; bj < 2; ++bj) {
;                             const f32x4 n0 = unpack4_raw(bj == 0 ? qa[ml].x : qa[ml].z), n1 = unpack4_raw(bj == 0 ? qa[ml].y : qa[ml].w);
;                             if (r < 2) { const f32x4 d0 = unpack4_raw(bj == 0 ? qb[ml].x : qb[ml].z), d1 = unpack4_raw(bj == 0 ? qb[ml].y : qb[ml].w);
; #pragma unroll
;                                 for (int j = 0; j < 4; ++j) { acc[ai][bj][m][0][j] *= n0[j] * __builtin_amdgcn_rcpf(d0[j]); acc[ai][bj][m][1][j] *= n1[j] * __builtin_amdgcn_rcpf(d1[j]); } }
;                             else { const f32x4 o0 = acc[ai][bj][m][0] * n0 * (1.0f / 255.0f), o1 = acc[ai][bj][m][1] * n1 * (1.0f / 255.0f);
;                                 *(u32x4*)(mg + (size_t)row * 1024 + u.pn * 256 + bj * 128 + cl) = pack8(o0, o1); } } }
;                     MEMFENCE; }
	v_cvt_f32_ubyte0_e32 v240, v200
	v_cvt_f32_ubyte1_e32 v241, v200
	v_cvt_f32_ubyte2_e32 v242, v200
	v_cvt_f32_ubyte3_e32 v243, v200
	v_cvt_f32_ubyte0_e32 v244, v201
	v_cvt_f32_ubyte1_e32 v245, v201
	v_cvt_f32_ubyte2_e32 v246, v201
	v_cvt_f32_ubyte3_e32 v247, v201
	v_pk_mul_f32 v[248:249], v[60:61], v[240:241]
	v_pk_mul_f32 v[250:251], v[62:63], v[242:243]
	v_pk_mul_f32 v[252:253], v[56:57], v[244:245]
	v_pk_mul_f32 v[254:255], v[58:59], v[246:247]
	v_pk_mul_f32 v[248:249], v[248:249], s[2:3] op_sel_hi:[1,0]
	v_pk_mul_f32 v[250:251], v[250:251], s[2:3] op_sel_hi:[1,0]
	v_pk_mul_f32 v[252:253], v[252:253], s[2:3] op_sel_hi:[1,0]
	v_pk_mul_f32 v[254:255], v[254:255], s[2:3] op_sel_hi:[1,0]
	v_cvt_pk_bf16_f32 v234, v248, v249
	v_cvt_pk_bf16_f32 v235, v250, v251
	v_cvt_pk_bf16_f32 v236, v252, v253
	v_cvt_pk_bf16_f32 v237, v254, v255
	global_store_dwordx4 v167, v[234:237], s[8:9]
	v_cvt_f32_ubyte0_e32 v240, v202
	v_cvt_f32_ubyte1_e32 v241, v202
	v_cvt_f32_ubyte2_e32 v242, v202
	v_cvt_f32_ubyte3_e32 v243, v202
	v_cvt_f32_ubyte0_e32 v244, v203
	v_cvt_f32_ubyte1_e32 v245, v203
	v_cvt_f32_ubyte2_e32 v246, v203
	v_cvt_f32_ubyte3_e32 v247, v203
	v_pk_mul_f32 v[248:249], v[28:29], v[240:241]
	v_pk_mul_f32 v[250:251], v[30:31], v[242:243]
	v_pk_mul_f32 v[252:253], v[24:25], v[244:245]
	v_pk_mul_f32 v[254:255], v[26:27], v[246:247]
	v_pk_mul_f32 v[248:249], v[248:249], s[2:3] op_sel_hi:[1,0]
	v_pk_mul_f32 v[250:251], v[250:251], s[2:3] op_sel_hi:[1,0]
	v_pk_mul_f32 v[252:253], v[252:253], s[2:3] op_sel_hi:[1,0]
	v_pk_mul_f32 v[254:255], v[254:255], s[2:3] op_sel_hi:[1,0]
	v_cvt_pk_bf16_f32 v234, v248, v249
	v_cvt_pk_bf16_f32 v235, v250, v251
	v_cvt_pk_bf16_f32 v236, v252, v253
	v_cvt_pk_bf16_f32 v237, v254, v255
	global_store_dwordx4 v167, v[234:237], s[8:9] offset:256
	s_add_u32 s8, s8, 0x8000
	s_addc_u32 s9, s9, 0
	s_waitcnt vmcnt(13)
	v_cvt_f32_ubyte0_e32 v240, v204
	v_cvt_f32_ubyte1_e32 v241, v204
	v_cvt_f32_ubyte2_e32 v242, v204
	v_cvt_f32_ubyte3_e32 v243, v204
	v_cvt_f32_ubyte0_e32 v244, v205
	v_cvt_f32_ubyte1_e32 v245, v205
	v_cvt_f32_ubyte2_e32 v246, v205
	v_cvt_f32_ubyte3_e32 v247, v205
	v_pk_mul_f32 v[248:249], v[52:53], v[240:241]
	v_pk_mul_f32 v[250:251], v[54:55], v[242:243]
	v_pk_mul_f32 v[252:253], v[48:49], v[244:245]
	v_pk_mul_f32 v[254:255], v[50:51], v[246:247]
	v_pk_mul_f32 v[248:249], v[248:249], s[2:3] op_sel_hi:[1,0]
	v_pk_mul_f32 v[250:251], v[250:251], s[2:3] op_sel_hi:[1,0]
	v_pk_mul_f32 v[252:253], v[252:253], s[2:3] op_sel_hi:[1,0]
	v_pk_mul_f32 v[254:255], v[254:255], s[2:3] op_sel_hi:[1,0]
	v_cvt_pk_bf16_f32 v234, v248, v249
	v_cvt_pk_bf16_f32 v235, v250, v251
	v_cvt_pk_bf16_f32 v236, v252, v253
	v_cvt_pk_bf16_f32 v237, v254, v255
	global_store_dwordx4 v167, v[234:237], s[8:9]
	v_cvt_f32_ubyte0_e32 v240, v206
	v_cvt_f32_ubyte1_e32 v241, v206
	v_cvt_f32_ubyte2_e32 v242, v206
	v_cvt_f32_ubyte3_e32 v243, v206
	v_cvt_f32_ubyte0_e32 v244, v207
	v_cvt_f32_ubyte1_e32 v245, v207
	v_cvt_f32_ubyte2_e32 v246, v207
	v_cvt_f32_ubyte3_e32 v247, v207
	v_pk_mul_f32 v[248:249], v[20:21], v[240:241]
	v_pk_mul_f32 v[250:251], v[22:23], v[242:243]
	v_pk_mul_f32 v[252:253], v[16:17], v[244:245]
	v_pk_mul_f32 v[254:255], v[18:19], v[246:247]
	v_pk_mul_f32 v[248:249], v[248:249], s[2:3] op_sel_hi:[1,0]
	v_pk_mul_f32 v[250:251], v[250:251], s[2:3] op_sel_hi:[1,0]
	v_pk_mul_f32 v[252:253], v[252:253], s[2:3] op_sel_hi:[1,0]
	v_pk_mul_f32 v[254:255], v[254:255], s[2:3] op_sel_hi:[1,0]
	v_cvt_pk_bf16_f32 v234, v248, v249
	v_cvt_pk_bf16_f32 v235, v250, v251
	v_cvt_pk_bf16_f32 v236, v252, v253
	v_cvt_pk_bf16_f32 v237, v254, v255
	global_store_dwordx4 v167, v[234:237], s[8:9] offset:256
	s_add_u32 s8, s8, 0x8000
	s_addc_u32 s9, s9, 0
	s_waitcnt vmcnt(14)
	v_cvt_f32_ubyte0_e32 v240, v208
	v_cvt_f32_ubyte1_e32 v241, v208
	v_cvt_f32_ubyte2_e32 v242, v208
	v_cvt_f32_ubyte3_e32 v243, v208
	v_cvt_f32_ubyte0_e32 v244, v209
	v_cvt_f32_ubyte1_e32 v245, v209
	v_cvt_f32_ubyte2_e32 v246, v209
	v_cvt_f32_ubyte3_e32 v247, v209
	v_pk_mul_f32 v[248:249], v[44:45], v[240:241]
	v_pk_mul_f32 v[250:251], v[46:47], v[242:243]
	v_pk_mul_f32 v[252:253], v[40:41], v[244:245]
	v_pk_mul_f32 v[254:255], v[42:43], v[246:247]
	v_pk_mul_f32 v[248:249], v[248:249], s[2:3] op_sel_hi:[1,0]
	v_pk_mul_f32 v[250:251], v[250:251], s[2:3] op_sel_hi:[1,0]
	v_pk_mul_f32 v[252:253], v[252:253], s[2:3] op_sel_hi:[1,0]
	v_pk_mul_f32 v[254:255], v[254:255], s[2:3] op_sel_hi:[1,0]
	v_cvt_pk_bf16_f32 v234, v248, v249
	v_cvt_pk_bf16_f32 v235, v250, v251
	v_cvt_pk_bf16_f32 v236, v252, v253
	v_cvt_pk_bf16_f32 v237, v254, v255
	global_store_dwordx4 v167, v[234:237], s[8:9]
	v_cvt_f32_ubyte0_e32 v240, v210
	v_cvt_f32_ubyte1_e32 v241, v210
	v_cvt_f32_ubyte2_e32 v242, v210
	v_cvt_f32_ubyte3_e32 v243, v210
	v_cvt_f32_ubyte0_e32 v244, v211
	v_cvt_f32_ubyte1_e32 v245, v211
	v_cvt_f32_ubyte2_e32 v246, v211
	v_cvt_f32_ubyte3_e32 v247, v211
	v_pk_mul_f32 v[248:249], v[12:13], v[240:241]
	v_pk_mul_f32 v[250:251], v[14:15], v[242:243]
	v_pk_mul_f32 v[252:253], v[8:9], v[244:245]
	v_pk_mul_f32 v[254:255], v[10:11], v[246:247]
	v_pk_mul_f32 v[248:249], v[248:249], s[2:3] op_sel_hi:[1,0]
	v_pk_mul_f32 v[250:251], v[250:251], s[2:3] op_sel_hi:[1,0]
	v_pk_mul_f32 v[252:253], v[252:253], s[2:3] op_sel_hi:[1,0]
	v_pk_mul_f32 v[254:255], v[254:255], s[2:3] op_sel_hi:[1,0]
	v_cvt_pk_bf16_f32 v234, v248, v249
	v_cvt_pk_bf16_f32 v235, v250, v251
	v_cvt_pk_bf16_f32 v236, v252, v253
	v_cvt_pk_bf16_f32 v237, v254, v255
	global_store_dwordx4 v167, v[234:237], s[8:9] offset:256
	s_mov_b64 s[6:7], 0
;     ...
;         E.template run<cs.kind>(acc, cur, tid);
;         if (!has_next) break;
;         if (!(cs.kind == K_MG_B && cur.aux < 2))
; #pragma unroll
;         for (int a = 0; a < 2; ++a)
; #pragma unroll
;             for (int b = 0; b < 2; ++b)
; #pragma unroll
;                 for (int m = 0; m < 4; ++m)
; #pragma unroll
;                     for (int n = 0; n < 2; ++n) acc[a][b][m][n] = (f32x4){0.f, 0.f, 0.f, 0.f};
;         cur = nxt; cA = nA; cB = nB; ++ui;
.Lmg1_done:
	v_readlane_b32 s44, v230, 7
	v_readlane_b32 s45, v230, 8
.LBB0_971:
	s_mov_b64 s[2:3], -1
	s_and_b64 vcc, exec, s[16:17]
	s_cbranch_vccz .LBB0_884
	s_and_b64 vcc, exec, s[6:7]
	s_cbranch_vccnz .LBB0_883
	v_mov_b32_e32 v2, v1
	v_mov_b32_e32 v3, v1
	v_mov_b32_e32 v0, v1
	v_mov_b64_e32 v[106:107], v[2:3]
	v_mov_b64_e32 v[110:111], v[2:3]
	v_mov_b64_e32 v[134:135], v[2:3]
	v_mov_b64_e32 v[130:131], v[2:3]
	v_mov_b64_e32 v[126:127], v[2:3]
	v_mov_b64_e32 v[122:123], v[2:3]
	v_mov_b64_e32 v[118:119], v[2:3]
	v_mov_b64_e32 v[114:115], v[2:3]
	v_mov_b64_e32 v[102:103], v[2:3]
	v_mov_b64_e32 v[98:99], v[2:3]
	v_mov_b64_e32 v[94:95], v[2:3]
	v_mov_b64_e32 v[90:91], v[2:3]
	v_mov_b64_e32 v[86:87], v[2:3]
	v_mov_b64_e32 v[82:83], v[2:3]
	v_mov_b64_e32 v[78:79], v[2:3]
	v_mov_b64_e32 v[74:75], v[2:3]
	v_mov_b64_e32 v[70:71], v[2:3]
	v_mov_b64_e32 v[66:67], v[2:3]
	v_mov_b64_e32 v[62:63], v[2:3]
	v_mov_b64_e32 v[58:59], v[2:3]
	v_mov_b64_e32 v[54:55], v[2:3]
	v_mov_b64_e32 v[50:51], v[2:3]
	v_mov_b64_e32 v[46:47], v[2:3]
	v_mov_b64_e32 v[42:43], v[2:3]
	v_mov_b64_e32 v[38:39], v[2:3]
	v_mov_b64_e32 v[34:35], v[2:3]
	v_mov_b64_e32 v[30:31], v[2:3]
	v_mov_b64_e32 v[26:27], v[2:3]
	v_mov_b64_e32 v[22:23], v[2:3]
	v_mov_b64_e32 v[18:19], v[2:3]
	v_mov_b64_e32 v[14:15], v[2:3]
	v_mov_b64_e32 v[10:11], v[2:3]
	v_mov_b64_e32 v[104:105], v[0:1]
	v_mov_b64_e32 v[108:109], v[0:1]
	v_mov_b64_e32 v[132:133], v[0:1]
	v_mov_b64_e32 v[128:129], v[0:1]
	v_mov_b64_e32 v[124:125], v[0:1]
	v_mov_b64_e32 v[120:121], v[0:1]
	v_mov_b64_e32 v[116:117], v[0:1]
	v_mov_b64_e32 v[112:113], v[0:1]
	v_mov_b64_e32 v[100:101], v[0:1]
	v_mov_b64_e32 v[96:97], v[0:1]
	v_mov_b64_e32 v[92:93], v[0:1]
	v_mov_b64_e32 v[88:89], v[0:1]
	v_mov_b64_e32 v[84:85], v[0:1]
	v_mov_b64_e32 v[80:81], v[0:1]
	v_mov_b64_e32 v[76:77], v[0:1]
	v_mov_b64_e32 v[72:73], v[0:1]
	v_mov_b64_e32 v[68:69], v[0:1]
	v_mov_b64_e32 v[64:65], v[0:1]
	v_mov_b64_e32 v[60:61], v[0:1]
	v_mov_b64_e32 v[56:57], v[0:1]
	v_mov_b64_e32 v[52:53], v[0:1]
	v_mov_b64_e32 v[48:49], v[0:1]
	v_mov_b64_e32 v[44:45], v[0:1]
	v_mov_b64_e32 v[40:41], v[0:1]
	v_mov_b64_e32 v[36:37], v[0:1]
	v_mov_b64_e32 v[32:33], v[0:1]
	v_mov_b64_e32 v[28:29], v[0:1]
	v_mov_b64_e32 v[24:25], v[0:1]
	v_mov_b64_e32 v[20:21], v[0:1]
	v_mov_b64_e32 v[16:17], v[0:1]
	v_mov_b64_e32 v[12:13], v[0:1]
	v_mov_b64_e32 v[8:9], v[0:1]
	s_branch .LBB0_883

; #define LAS __attribute__((address_space(3)))
; __global__ void __launch_bounds__(512) fwd_megakernel(Params Parg) {
;     ...
;     cg::grid_group grid = cg::this_grid();
;     extern __shared__ __attribute__((aligned(16))) unsigned char smem[];
;     LAS unsigned char* lds = (LAS unsigned char*)smem;
	.amdhsa_kernel _Z14fwd_megakernel6Params
		.amdhsa_group_segment_fixed_size 0
		.amdhsa_private_segment_fixed_size 0
		.amdhsa_kernarg_size 472
		.amdhsa_user_sgpr_count 2
		.amdhsa_user_sgpr_dispatch_ptr 0
		.amdhsa_user_sgpr_queue_ptr 0
		.amdhsa_user_sgpr_kernarg_segment_ptr 1
		.amdhsa_user_sgpr_dispatch_id 0
		.amdhsa_user_sgpr_kernarg_preload_length 0
		.amdhsa_user_sgpr_kernarg_preload_offset 0
		.amdhsa_user_sgpr_private_segment_size 0
		.amdhsa_uses_dynamic_stack 0
		.amdhsa_enable_private_segment 0
		.amdhsa_system_sgpr_workgroup_id_x 1
		.amdhsa_system_sgpr_workgroup_id_y 0
		.amdhsa_system_sgpr_workgroup_id_z 0
		.amdhsa_system_sgpr_workgroup_info 0
		.amdhsa_system_vgpr_workitem_id 2
		.amdhsa_next_free_vgpr 256
		.amdhsa_next_free_sgpr 100
		.amdhsa_accum_offset 256
		.amdhsa_reserve_vcc 1
		.amdhsa_float_round_mode_32 0
		.amdhsa_float_round_mode_16_64 0
		.amdhsa_float_denorm_mode_32 3
		.amdhsa_float_denorm_mode_16_64 3
		.amdhsa_dx10_clamp 1
		.amdhsa_ieee_mode 1
		.amdhsa_fp16_overflow 0
		.amdhsa_tg_split 0
		.amdhsa_exception_fp_ieee_invalid_op 0
		.amdhsa_exception_fp_denorm_src 0
		.amdhsa_exception_fp_ieee_div_zero 0
		.amdhsa_exception_fp_ieee_overflow 0
		.amdhsa_exception_fp_ieee_underflow 0
		.amdhsa_exception_fp_ieee_inexact 0
		.amdhsa_exception_int_div_zero 0
	.end_amdhsa_kernel

; #define LAS __attribute__((address_space(3)))
; __global__ void __launch_bounds__(512) fwd_megakernel(Params Parg) {
;     ...
;     cg::grid_group grid = cg::this_grid();
;     extern __shared__ __attribute__((aligned(16))) unsigned char smem[];
;     LAS unsigned char* lds = (LAS unsigned char*)smem;
amdhsa.kernels:
  - .agpr_count:     0
    .args:
      - .offset:         0
        .size:           216
        .value_kind:     by_value
      - .offset:         216
        .size:           4
        .value_kind:     hidden_block_count_x
      - .offset:         220
        .size:           4
        .value_kind:     hidden_block_count_y
      - .offset:         224
        .size:           4
        .value_kind:     hidden_block_count_z
      - .offset:         228
        .size:           2
        .value_kind:     hidden_group_size_x
      - .offset:         230
        .size:           2
        .value_kind:     hidden_group_size_y
      - .offset:         232
        .size:           2
        .value_kind:     hidden_group_size_z
      - .offset:         234
        .size:           2
        .value_kind:     hidden_remainder_x
      - .offset:         236
        .size:           2
        .value_kind:     hidden_remainder_y
      - .offset:         238
        .size:           2
        .value_kind:     hidden_remainder_z
      - .offset:         256
        .size:           8
        .value_kind:     hidden_global_offset_x
      - .offset:         264
        .size:           8
        .value_kind:     hidden_global_offset_y
      - .offset:         272
        .size:           8
        .value_kind:     hidden_global_offset_z
      - .offset:         280
        .size:           2
        .value_kind:     hidden_grid_dims
      - .offset:         304
        .size:           8
        .value_kind:     hidden_multigrid_sync_arg
      - .offset:         336
        .size:           4
        .value_kind:     hidden_dynamic_lds_size
    .group_segment_fixed_size: 0
    .kernarg_segment_align: 8
    .kernarg_segment_size: 472
    .language:       OpenCL C
    .language_version:
      - 2
      - 0
    .max_flat_workgroup_size: 512
    .name:           _Z14fwd_megakernel6Params
    .private_segment_fixed_size: 0
    .sgpr_count:     106
    .sgpr_spill_count: 328
    .symbol:         _Z14fwd_megakernel6Params.kd
    .uniform_work_group_size: 1
    .uses_dynamic_stack: false
    .vgpr_count:     256
    .vgpr_spill_count: 0
    .wavefront_size: 64
